# GEMM K-loops without the per-MFMA-block s_setprio 1/0 toggles (priority 0 throughout P1/P4/P6/P7/P8)
# speedup vs baseline: 1.0088x; 1.0048x over previous
.LBB0_163:
	ds_read_b128 v[148:151], v155
	ds_read_b128 v[160:163], v155 offset:1024
	ds_read_b128 v[164:167], v155 offset:2048
	ds_read_b128 v[168:171], v155 offset:3072
	ds_read_b128 v[172:175], v156
	ds_read_b128 v[176:179], v156 offset:1024
	ds_read_b128 v[180:183], v156 offset:2048
	ds_read_b128 v[184:187], v156 offset:3072
	s_add_u32 s44, s8, 0xfffc0080
	s_addc_u32 s45, s9, -1
	s_cmp_eq_u32 s50, 12
	s_cselect_b32 s47, s5, s45
	s_cselect_b32 s46, s7, s44
	s_cselect_b32 s45, s37, s49
	s_cselect_b32 s44, s39, s48
	v_lshl_add_u64 v[222:223], s[8:9], 0, v[138:139]
	s_add_i32 m0, s20, 0xc000
	ds_read_b128 v[188:191], v157
	ds_read_b128 v[194:197], v157 offset:1024
	ds_read_b128 v[198:201], v157 offset:2048
	ds_read_b128 v[202:205], v157 offset:3072
	ds_read_b128 v[206:209], v157 offset:4096
	ds_read_b128 v[210:213], v157 offset:5120
	ds_read_b128 v[214:217], v157 offset:6144
	ds_read_b128 v[218:221], v157 offset:7168
	global_load_lds_dwordx4 v[222:223], off
	v_lshl_add_u64 v[222:223], s[8:9], 0, v[140:141]
	s_add_i32 m0, s20, 0xe000
	s_nop 0
	global_load_lds_dwordx4 v[222:223], off
	s_waitcnt vmcnt(8)
	s_waitcnt lgkmcnt(0)
	s_barrier
	s_waitcnt lgkmcnt(0)
	v_mfma_f32_16x16x32_bf16 v[124:127], v[148:151], v[188:191], v[124:127]
	v_mfma_f32_16x16x32_bf16 v[120:123], v[164:167], v[188:191], v[120:123]
	v_mfma_f32_16x16x32_bf16 v[108:111], v[148:151], v[198:201], v[108:111]
	v_mfma_f32_16x16x32_bf16 v[104:107], v[164:167], v[198:201], v[104:107]
	v_mfma_f32_16x16x32_bf16 v[96:99], v[148:151], v[206:209], v[96:99]
	v_mfma_f32_16x16x32_bf16 v[88:91], v[164:167], v[206:209], v[88:91]
	v_mfma_f32_16x16x32_bf16 v[84:87], v[148:151], v[214:217], v[84:87]
	v_mfma_f32_16x16x32_bf16 v[76:79], v[164:167], v[214:217], v[76:79]
	v_mfma_f32_16x16x32_bf16 v[124:127], v[160:163], v[194:197], v[124:127]
	v_mfma_f32_16x16x32_bf16 v[120:123], v[168:171], v[194:197], v[120:123]
	v_mfma_f32_16x16x32_bf16 v[108:111], v[160:163], v[202:205], v[108:111]
	v_mfma_f32_16x16x32_bf16 v[104:107], v[168:171], v[202:205], v[104:107]
	v_mfma_f32_16x16x32_bf16 v[96:99], v[160:163], v[210:213], v[96:99]
	v_mfma_f32_16x16x32_bf16 v[88:91], v[168:171], v[210:213], v[88:91]
	v_mfma_f32_16x16x32_bf16 v[84:87], v[160:163], v[218:221], v[84:87]
	v_mfma_f32_16x16x32_bf16 v[76:79], v[168:171], v[218:221], v[76:79]
	v_mfma_f32_16x16x32_bf16 v[116:119], v[172:175], v[188:191], v[116:119]
	v_mfma_f32_16x16x32_bf16 v[112:115], v[180:183], v[188:191], v[112:115]
	v_mfma_f32_16x16x32_bf16 v[100:103], v[172:175], v[198:201], v[100:103]
	v_mfma_f32_16x16x32_bf16 v[92:95], v[180:183], v[198:201], v[92:95]
	v_mfma_f32_16x16x32_bf16 v[80:83], v[172:175], v[206:209], v[80:83]
	v_mfma_f32_16x16x32_bf16 v[72:75], v[180:183], v[206:209], v[72:75]
	v_mfma_f32_16x16x32_bf16 v[68:71], v[172:175], v[214:217], v[68:71]
	v_mfma_f32_16x16x32_bf16 v[64:67], v[180:183], v[214:217], v[64:67]
	v_mfma_f32_16x16x32_bf16 v[116:119], v[176:179], v[194:197], v[116:119]
	v_mfma_f32_16x16x32_bf16 v[112:115], v[184:187], v[194:197], v[112:115]
	v_mfma_f32_16x16x32_bf16 v[100:103], v[176:179], v[202:205], v[100:103]
	v_mfma_f32_16x16x32_bf16 v[92:95], v[184:187], v[202:205], v[92:95]
	v_mfma_f32_16x16x32_bf16 v[80:83], v[176:179], v[210:213], v[80:83]
	v_mfma_f32_16x16x32_bf16 v[72:75], v[184:187], v[210:213], v[72:75]
	v_mfma_f32_16x16x32_bf16 v[68:71], v[176:179], v[218:221], v[68:71]
	v_mfma_f32_16x16x32_bf16 v[64:67], v[184:187], v[218:221], v[64:67]
	s_barrier
	s_add_i32 s51, s72, s15
	v_lshl_add_u64 v[222:223], s[44:45], 0, v[130:131]
	s_mov_b32 m0, s51
	ds_read_b128 v[188:191], v157 offset:16384
	ds_read_b128 v[194:197], v157 offset:17408
	ds_read_b128 v[198:201], v157 offset:18432
	ds_read_b128 v[202:205], v157 offset:19456
	ds_read_b128 v[206:209], v157 offset:20480
	ds_read_b128 v[210:213], v157 offset:21504
	ds_read_b128 v[214:217], v157 offset:22528
	ds_read_b128 v[218:221], v157 offset:23552
	global_load_lds_dwordx4 v[222:223], off
	s_add_i32 m0, s51, 0x2000
	s_add_u32 s64, s44, 0x40000
	v_lshl_add_u64 v[224:225], s[44:45], 0, v[134:135]
	s_addc_u32 s65, s45, 0
	s_add_i32 s51, s73, s15
	global_load_lds_dwordx4 v[224:225], off
	v_lshl_add_u64 v[226:227], s[64:65], 0, v[130:131]
	s_mov_b32 m0, s51
	v_lshl_add_u64 v[228:229], s[46:47], 0, v[132:133]
	global_load_lds_dwordx4 v[226:227], off
	v_lshl_add_u64 v[226:227], s[64:65], 0, v[134:135]
	s_add_i32 m0, s51, 0x2000
	s_nop 0
	global_load_lds_dwordx4 v[226:227], off
	v_lshl_add_u64 v[226:227], s[46:47], 0, v[128:129]
	s_mov_b32 m0, s20
	s_nop 0
	global_load_lds_dwordx4 v[226:227], off
	s_mov_b32 m0, s21
	s_nop 0
	global_load_lds_dwordx4 v[228:229], off
	s_waitcnt vmcnt(8)
	s_waitcnt lgkmcnt(0)
	s_barrier
	s_waitcnt lgkmcnt(0)
	v_mfma_f32_16x16x32_bf16 v[60:63], v[148:151], v[188:191], v[60:63]
	v_mfma_f32_16x16x32_bf16 v[56:59], v[164:167], v[188:191], v[56:59]
	v_mfma_f32_16x16x32_bf16 v[44:47], v[148:151], v[198:201], v[44:47]
	v_mfma_f32_16x16x32_bf16 v[40:43], v[164:167], v[198:201], v[40:43]
	v_mfma_f32_16x16x32_bf16 v[32:35], v[148:151], v[206:209], v[32:35]
	v_mfma_f32_16x16x32_bf16 v[24:27], v[164:167], v[206:209], v[24:27]
	v_mfma_f32_16x16x32_bf16 v[20:23], v[148:151], v[214:217], v[20:23]
	v_mfma_f32_16x16x32_bf16 v[12:15], v[164:167], v[214:217], v[12:15]
	v_mfma_f32_16x16x32_bf16 v[60:63], v[160:163], v[194:197], v[60:63]
	v_mfma_f32_16x16x32_bf16 v[56:59], v[168:171], v[194:197], v[56:59]
	v_mfma_f32_16x16x32_bf16 v[44:47], v[160:163], v[202:205], v[44:47]
	v_mfma_f32_16x16x32_bf16 v[40:43], v[168:171], v[202:205], v[40:43]
	v_mfma_f32_16x16x32_bf16 v[32:35], v[160:163], v[210:213], v[32:35]
	v_mfma_f32_16x16x32_bf16 v[24:27], v[168:171], v[210:213], v[24:27]
	v_mfma_f32_16x16x32_bf16 v[20:23], v[160:163], v[218:221], v[20:23]
	v_mfma_f32_16x16x32_bf16 v[12:15], v[168:171], v[218:221], v[12:15]
	v_mfma_f32_16x16x32_bf16 v[52:55], v[172:175], v[188:191], v[52:55]
	v_mfma_f32_16x16x32_bf16 v[48:51], v[180:183], v[188:191], v[48:51]
	v_mfma_f32_16x16x32_bf16 v[36:39], v[172:175], v[198:201], v[36:39]
	v_mfma_f32_16x16x32_bf16 v[28:31], v[180:183], v[198:201], v[28:31]
	v_mfma_f32_16x16x32_bf16 v[16:19], v[172:175], v[206:209], v[16:19]
	v_mfma_f32_16x16x32_bf16 v[8:11], v[180:183], v[206:209], v[8:11]
	v_mfma_f32_16x16x32_bf16 v[4:7], v[172:175], v[214:217], v[4:7]
	v_mfma_f32_16x16x32_bf16 v[0:3], v[180:183], v[214:217], v[0:3]
	v_mfma_f32_16x16x32_bf16 v[52:55], v[176:179], v[194:197], v[52:55]
	v_mfma_f32_16x16x32_bf16 v[48:51], v[184:187], v[194:197], v[48:51]
	v_mfma_f32_16x16x32_bf16 v[36:39], v[176:179], v[202:205], v[36:39]
	v_mfma_f32_16x16x32_bf16 v[28:31], v[184:187], v[202:205], v[28:31]
	v_mfma_f32_16x16x32_bf16 v[16:19], v[176:179], v[210:213], v[16:19]
	v_mfma_f32_16x16x32_bf16 v[8:11], v[184:187], v[210:213], v[8:11]
	v_mfma_f32_16x16x32_bf16 v[4:7], v[176:179], v[218:221], v[4:7]
	v_mfma_f32_16x16x32_bf16 v[0:3], v[184:187], v[218:221], v[0:3]
	s_barrier
	s_add_i32 s51, 0, 0x18000
	v_add_u32_e32 v136, s51, v154
	s_add_i32 s64, 0, 0x1c000
	ds_read_b128 v[148:151], v136
	ds_read_b128 v[160:163], v136 offset:1024
	ds_read_b128 v[164:167], v136 offset:2048
	ds_read_b128 v[168:171], v136 offset:3072
	v_add_u32_e32 v136, s64, v154
	ds_read_b128 v[172:175], v136
	ds_read_b128 v[176:179], v136 offset:1024
	ds_read_b128 v[180:183], v136 offset:2048
	ds_read_b128 v[184:187], v136 offset:3072
	s_add_u32 s46, s46, 0x40000
	s_addc_u32 s47, s47, 0
	s_mov_b32 m0, s22
	v_lshl_add_u64 v[230:231], s[46:47], 0, v[128:129]
	ds_read_b128 v[188:191], v157 offset:32768
	ds_read_b128 v[194:197], v157 offset:33792
	ds_read_b128 v[198:201], v157 offset:34816
	ds_read_b128 v[202:205], v157 offset:35840
	ds_read_b128 v[206:209], v157 offset:36864
	ds_read_b128 v[210:213], v157 offset:37888
	ds_read_b128 v[214:217], v157 offset:38912
	ds_read_b128 v[218:221], v157 offset:39936
	global_load_lds_dwordx4 v[230:231], off
	v_lshl_add_u64 v[230:231], s[46:47], 0, v[132:133]
	s_mov_b32 m0, s23
	s_nop 0
	global_load_lds_dwordx4 v[230:231], off
	s_waitcnt vmcnt(8)
	s_waitcnt lgkmcnt(0)
	s_barrier
	s_waitcnt lgkmcnt(0)
	v_mfma_f32_16x16x32_bf16 v[124:127], v[148:151], v[188:191], v[124:127]
	v_mfma_f32_16x16x32_bf16 v[120:123], v[164:167], v[188:191], v[120:123]
	v_mfma_f32_16x16x32_bf16 v[108:111], v[148:151], v[198:201], v[108:111]
	v_mfma_f32_16x16x32_bf16 v[104:107], v[164:167], v[198:201], v[104:107]
	v_mfma_f32_16x16x32_bf16 v[96:99], v[148:151], v[206:209], v[96:99]
	v_mfma_f32_16x16x32_bf16 v[88:91], v[164:167], v[206:209], v[88:91]
	v_mfma_f32_16x16x32_bf16 v[84:87], v[148:151], v[214:217], v[84:87]
	v_mfma_f32_16x16x32_bf16 v[76:79], v[164:167], v[214:217], v[76:79]
	v_mfma_f32_16x16x32_bf16 v[124:127], v[160:163], v[194:197], v[124:127]
	v_mfma_f32_16x16x32_bf16 v[120:123], v[168:171], v[194:197], v[120:123]
	v_mfma_f32_16x16x32_bf16 v[108:111], v[160:163], v[202:205], v[108:111]
	v_mfma_f32_16x16x32_bf16 v[104:107], v[168:171], v[202:205], v[104:107]
	v_mfma_f32_16x16x32_bf16 v[96:99], v[160:163], v[210:213], v[96:99]
	v_mfma_f32_16x16x32_bf16 v[88:91], v[168:171], v[210:213], v[88:91]
	v_mfma_f32_16x16x32_bf16 v[84:87], v[160:163], v[218:221], v[84:87]
	v_mfma_f32_16x16x32_bf16 v[76:79], v[168:171], v[218:221], v[76:79]
	v_mfma_f32_16x16x32_bf16 v[116:119], v[172:175], v[188:191], v[116:119]
	v_mfma_f32_16x16x32_bf16 v[112:115], v[180:183], v[188:191], v[112:115]
	v_mfma_f32_16x16x32_bf16 v[100:103], v[172:175], v[198:201], v[100:103]
	v_mfma_f32_16x16x32_bf16 v[92:95], v[180:183], v[198:201], v[92:95]
	v_mfma_f32_16x16x32_bf16 v[80:83], v[172:175], v[206:209], v[80:83]
	v_mfma_f32_16x16x32_bf16 v[72:75], v[180:183], v[206:209], v[72:75]
	v_mfma_f32_16x16x32_bf16 v[68:71], v[172:175], v[214:217], v[68:71]
	v_mfma_f32_16x16x32_bf16 v[64:67], v[180:183], v[214:217], v[64:67]
	v_mfma_f32_16x16x32_bf16 v[116:119], v[176:179], v[194:197], v[116:119]
	v_mfma_f32_16x16x32_bf16 v[112:115], v[184:187], v[194:197], v[112:115]
	v_mfma_f32_16x16x32_bf16 v[100:103], v[176:179], v[202:205], v[100:103]
	v_mfma_f32_16x16x32_bf16 v[92:95], v[184:187], v[202:205], v[92:95]
	v_mfma_f32_16x16x32_bf16 v[80:83], v[176:179], v[210:213], v[80:83]
	v_mfma_f32_16x16x32_bf16 v[72:75], v[184:187], v[210:213], v[72:75]
	v_mfma_f32_16x16x32_bf16 v[68:71], v[176:179], v[218:221], v[68:71]
	v_mfma_f32_16x16x32_bf16 v[64:67], v[184:187], v[218:221], v[64:67]
	s_barrier
	s_add_i32 s46, s51, s15
	v_lshl_add_u64 v[222:223], v[222:223], 0, s[18:19]
	s_mov_b32 m0, s46
	ds_read_b128 v[188:191], v157 offset:49152
	ds_read_b128 v[194:197], v157 offset:50176
	ds_read_b128 v[198:201], v157 offset:51200
	ds_read_b128 v[202:205], v157 offset:52224
	ds_read_b128 v[206:209], v157 offset:53248
	ds_read_b128 v[210:213], v157 offset:54272
	ds_read_b128 v[214:217], v157 offset:55296
	ds_read_b128 v[218:221], v157 offset:56320
	global_load_lds_dwordx4 v[222:223], off
	s_add_i32 m0, s46, 0x2000
	s_add_u32 s44, s44, 0x40080
	v_lshl_add_u64 v[222:223], v[224:225], 0, s[18:19]
	s_addc_u32 s45, s45, 0
	s_add_i32 s46, s64, s15
	global_load_lds_dwordx4 v[222:223], off
	v_lshl_add_u64 v[222:223], s[44:45], 0, v[130:131]
	s_mov_b32 m0, s46
	s_nop 0
	global_load_lds_dwordx4 v[222:223], off
	v_lshl_add_u64 v[222:223], s[44:45], 0, v[134:135]
	s_add_i32 m0, s46, 0x2000
	s_nop 0
	global_load_lds_dwordx4 v[222:223], off
	v_lshl_add_u64 v[222:223], v[226:227], 0, s[18:19]
	s_mov_b32 m0, s70
	s_nop 0
	global_load_lds_dwordx4 v[222:223], off
	v_lshl_add_u64 v[222:223], v[228:229], 0, s[18:19]
	s_mov_b32 m0, s71
	s_nop 0
	global_load_lds_dwordx4 v[222:223], off
	s_waitcnt vmcnt(8)
	s_waitcnt lgkmcnt(0)
	s_barrier
	s_waitcnt lgkmcnt(0)
	v_mfma_f32_16x16x32_bf16 v[60:63], v[148:151], v[188:191], v[60:63]
	v_mfma_f32_16x16x32_bf16 v[56:59], v[164:167], v[188:191], v[56:59]
	v_mfma_f32_16x16x32_bf16 v[44:47], v[148:151], v[198:201], v[44:47]
	v_mfma_f32_16x16x32_bf16 v[40:43], v[164:167], v[198:201], v[40:43]
	v_mfma_f32_16x16x32_bf16 v[32:35], v[148:151], v[206:209], v[32:35]
	v_mfma_f32_16x16x32_bf16 v[24:27], v[164:167], v[206:209], v[24:27]
	v_mfma_f32_16x16x32_bf16 v[20:23], v[148:151], v[214:217], v[20:23]
	v_mfma_f32_16x16x32_bf16 v[12:15], v[164:167], v[214:217], v[12:15]
	v_mfma_f32_16x16x32_bf16 v[60:63], v[160:163], v[194:197], v[60:63]
	v_mfma_f32_16x16x32_bf16 v[56:59], v[168:171], v[194:197], v[56:59]
	v_mfma_f32_16x16x32_bf16 v[44:47], v[160:163], v[202:205], v[44:47]
	v_mfma_f32_16x16x32_bf16 v[40:43], v[168:171], v[202:205], v[40:43]
	v_mfma_f32_16x16x32_bf16 v[32:35], v[160:163], v[210:213], v[32:35]
	v_mfma_f32_16x16x32_bf16 v[24:27], v[168:171], v[210:213], v[24:27]
	v_mfma_f32_16x16x32_bf16 v[20:23], v[160:163], v[218:221], v[20:23]
	v_mfma_f32_16x16x32_bf16 v[12:15], v[168:171], v[218:221], v[12:15]
	v_mfma_f32_16x16x32_bf16 v[52:55], v[172:175], v[188:191], v[52:55]
	v_mfma_f32_16x16x32_bf16 v[48:51], v[180:183], v[188:191], v[48:51]
	v_mfma_f32_16x16x32_bf16 v[36:39], v[172:175], v[198:201], v[36:39]
	v_mfma_f32_16x16x32_bf16 v[28:31], v[180:183], v[198:201], v[28:31]
	v_mfma_f32_16x16x32_bf16 v[16:19], v[172:175], v[206:209], v[16:19]
	v_mfma_f32_16x16x32_bf16 v[8:11], v[180:183], v[206:209], v[8:11]
	v_mfma_f32_16x16x32_bf16 v[4:7], v[172:175], v[214:217], v[4:7]
	v_mfma_f32_16x16x32_bf16 v[0:3], v[180:183], v[214:217], v[0:3]
	v_mfma_f32_16x16x32_bf16 v[52:55], v[176:179], v[194:197], v[52:55]
	v_mfma_f32_16x16x32_bf16 v[48:51], v[184:187], v[194:197], v[48:51]
	v_mfma_f32_16x16x32_bf16 v[36:39], v[176:179], v[202:205], v[36:39]
	v_mfma_f32_16x16x32_bf16 v[28:31], v[184:187], v[202:205], v[28:31]
	v_mfma_f32_16x16x32_bf16 v[16:19], v[176:179], v[210:213], v[16:19]
	v_mfma_f32_16x16x32_bf16 v[8:11], v[184:187], v[210:213], v[8:11]
	v_mfma_f32_16x16x32_bf16 v[4:7], v[176:179], v[218:221], v[4:7]
	v_mfma_f32_16x16x32_bf16 v[0:3], v[184:187], v[218:221], v[0:3]
	s_barrier
	s_add_i32 s50, s50, 2
	s_add_u32 s8, s8, 0x100
	s_addc_u32 s9, s9, 0
	s_add_u32 s48, s48, 0x100
	s_addc_u32 s49, s49, 0
	s_cmp_gt_u32 s50, 13
	s_cbranch_scc0 .LBB0_163
	s_and_b64 vcc, exec, s[34:35]
	s_cbranch_vccz .LBB0_166
	s_barrier

.LBB0_640:
	ds_read_b128 v[170:173], v164
	ds_read_b128 v[174:177], v164 offset:1024
	ds_read_b128 v[178:181], v164 offset:2048
	ds_read_b128 v[182:185], v164 offset:3072
	ds_read_b128 v[186:189], v165
	ds_read_b128 v[194:197], v165 offset:1024
	ds_read_b128 v[198:201], v165 offset:2048
	ds_read_b128 v[202:205], v165 offset:3072
	s_add_u32 s42, s36, 0xfffc0080
	s_addc_u32 s43, s37, -1
	s_cmp_eq_u32 s71, 12
	s_cselect_b32 s47, s13, s43
	s_cselect_b32 s46, s67, s42
	s_cselect_b32 s43, s11, s70
	s_cselect_b32 s42, s68, s69
	v_lshl_add_u64 v[148:149], s[36:37], 0, v[138:139]
	s_add_i32 m0, s22, 0xc000
	ds_read_b128 v[206:209], v166
	ds_read_b128 v[210:213], v166 offset:1024
	ds_read_b128 v[214:217], v166 offset:2048
	ds_read_b128 v[218:221], v166 offset:3072
	ds_read_b128 v[222:225], v166 offset:4096
	ds_read_b128 v[226:229], v166 offset:5120
	ds_read_b128 v[230:233], v166 offset:6144
	ds_read_b128 v[234:237], v166 offset:7168
	global_load_lds_dwordx4 v[148:149], off
	v_lshl_add_u64 v[148:149], s[36:37], 0, v[140:141]
	s_add_i32 m0, s22, 0xe000
	s_nop 0
	global_load_lds_dwordx4 v[148:149], off
	s_waitcnt vmcnt(8)
	s_waitcnt lgkmcnt(0)
	s_barrier
	s_waitcnt lgkmcnt(0)
	v_mfma_f32_16x16x32_bf16 v[124:127], v[170:173], v[206:209], v[124:127]
	v_mfma_f32_16x16x32_bf16 v[120:123], v[178:181], v[206:209], v[120:123]
	v_mfma_f32_16x16x32_bf16 v[116:119], v[170:173], v[214:217], v[116:119]
	v_mfma_f32_16x16x32_bf16 v[112:115], v[178:181], v[214:217], v[112:115]
	v_mfma_f32_16x16x32_bf16 v[100:103], v[170:173], v[222:225], v[100:103]
	v_mfma_f32_16x16x32_bf16 v[96:99], v[178:181], v[222:225], v[96:99]
	v_mfma_f32_16x16x32_bf16 v[84:87], v[170:173], v[230:233], v[84:87]
	v_mfma_f32_16x16x32_bf16 v[80:83], v[178:181], v[230:233], v[80:83]
	v_mfma_f32_16x16x32_bf16 v[124:127], v[174:177], v[210:213], v[124:127]
	v_mfma_f32_16x16x32_bf16 v[120:123], v[182:185], v[210:213], v[120:123]
	v_mfma_f32_16x16x32_bf16 v[116:119], v[174:177], v[218:221], v[116:119]
	v_mfma_f32_16x16x32_bf16 v[112:115], v[182:185], v[218:221], v[112:115]
	v_mfma_f32_16x16x32_bf16 v[100:103], v[174:177], v[226:229], v[100:103]
	v_mfma_f32_16x16x32_bf16 v[96:99], v[182:185], v[226:229], v[96:99]
	v_mfma_f32_16x16x32_bf16 v[84:87], v[174:177], v[234:237], v[84:87]
	v_mfma_f32_16x16x32_bf16 v[80:83], v[182:185], v[234:237], v[80:83]
	v_mfma_f32_16x16x32_bf16 v[108:111], v[186:189], v[206:209], v[108:111]
	v_mfma_f32_16x16x32_bf16 v[104:107], v[198:201], v[206:209], v[104:107]
	v_mfma_f32_16x16x32_bf16 v[92:95], v[186:189], v[214:217], v[92:95]
	v_mfma_f32_16x16x32_bf16 v[88:91], v[198:201], v[214:217], v[88:91]
	v_mfma_f32_16x16x32_bf16 v[76:79], v[186:189], v[222:225], v[76:79]
	v_mfma_f32_16x16x32_bf16 v[72:75], v[198:201], v[222:225], v[72:75]
	v_mfma_f32_16x16x32_bf16 v[68:71], v[186:189], v[230:233], v[68:71]
	v_mfma_f32_16x16x32_bf16 v[64:67], v[198:201], v[230:233], v[64:67]
	v_mfma_f32_16x16x32_bf16 v[108:111], v[194:197], v[210:213], v[108:111]
	v_mfma_f32_16x16x32_bf16 v[104:107], v[202:205], v[210:213], v[104:107]
	v_mfma_f32_16x16x32_bf16 v[92:95], v[194:197], v[218:221], v[92:95]
	v_mfma_f32_16x16x32_bf16 v[88:91], v[202:205], v[218:221], v[88:91]
	v_mfma_f32_16x16x32_bf16 v[76:79], v[194:197], v[226:229], v[76:79]
	v_mfma_f32_16x16x32_bf16 v[72:75], v[202:205], v[226:229], v[72:75]
	v_mfma_f32_16x16x32_bf16 v[68:71], v[194:197], v[234:237], v[68:71]
	v_mfma_f32_16x16x32_bf16 v[64:67], v[202:205], v[234:237], v[64:67]
	s_barrier
	s_add_i32 s72, s65, s14
	v_lshl_add_u64 v[148:149], s[42:43], 0, v[132:133]
	s_mov_b32 m0, s72
	ds_read_b128 v[206:209], v166 offset:16384
	ds_read_b128 v[210:213], v166 offset:17408
	ds_read_b128 v[214:217], v166 offset:18432
	ds_read_b128 v[218:221], v166 offset:19456
	ds_read_b128 v[222:225], v166 offset:20480
	ds_read_b128 v[226:229], v166 offset:21504
	ds_read_b128 v[230:233], v166 offset:22528
	ds_read_b128 v[234:237], v166 offset:23552
	global_load_lds_dwordx4 v[148:149], off
	s_add_i32 m0, s72, 0x2000
	s_add_u32 s72, s42, 0x40000
	v_lshl_add_u64 v[190:191], s[42:43], 0, v[128:129]
	s_addc_u32 s73, s43, 0
	s_add_i32 s78, s66, s14
	global_load_lds_dwordx4 v[190:191], off
	v_lshl_add_u64 v[238:239], s[72:73], 0, v[132:133]
	s_mov_b32 m0, s78
	v_lshl_add_u64 v[240:241], s[46:47], 0, v[130:131]
	global_load_lds_dwordx4 v[238:239], off
	v_lshl_add_u64 v[238:239], s[72:73], 0, v[128:129]
	s_add_i32 m0, s78, 0x2000
	s_nop 0
	global_load_lds_dwordx4 v[238:239], off
	v_lshl_add_u64 v[238:239], s[46:47], 0, v[134:135]
	s_mov_b32 m0, s22
	s_nop 0
	global_load_lds_dwordx4 v[238:239], off
	s_mov_b32 m0, s23
	s_nop 0
	global_load_lds_dwordx4 v[240:241], off
	s_waitcnt vmcnt(8)
	s_waitcnt lgkmcnt(0)
	s_barrier
	s_waitcnt lgkmcnt(0)
	v_mfma_f32_16x16x32_bf16 v[60:63], v[170:173], v[206:209], v[60:63]
	v_mfma_f32_16x16x32_bf16 v[56:59], v[178:181], v[206:209], v[56:59]
	v_mfma_f32_16x16x32_bf16 v[52:55], v[170:173], v[214:217], v[52:55]
	v_mfma_f32_16x16x32_bf16 v[48:51], v[178:181], v[214:217], v[48:51]
	v_mfma_f32_16x16x32_bf16 v[36:39], v[170:173], v[222:225], v[36:39]
	v_mfma_f32_16x16x32_bf16 v[32:35], v[178:181], v[222:225], v[32:35]
	v_mfma_f32_16x16x32_bf16 v[20:23], v[170:173], v[230:233], v[20:23]
	v_mfma_f32_16x16x32_bf16 v[16:19], v[178:181], v[230:233], v[16:19]
	v_mfma_f32_16x16x32_bf16 v[60:63], v[174:177], v[210:213], v[60:63]
	v_mfma_f32_16x16x32_bf16 v[56:59], v[182:185], v[210:213], v[56:59]
	v_mfma_f32_16x16x32_bf16 v[52:55], v[174:177], v[218:221], v[52:55]
	v_mfma_f32_16x16x32_bf16 v[48:51], v[182:185], v[218:221], v[48:51]
	v_mfma_f32_16x16x32_bf16 v[36:39], v[174:177], v[226:229], v[36:39]
	v_mfma_f32_16x16x32_bf16 v[32:35], v[182:185], v[226:229], v[32:35]
	v_mfma_f32_16x16x32_bf16 v[20:23], v[174:177], v[234:237], v[20:23]
	v_mfma_f32_16x16x32_bf16 v[16:19], v[182:185], v[234:237], v[16:19]
	v_mfma_f32_16x16x32_bf16 v[44:47], v[186:189], v[206:209], v[44:47]
	v_mfma_f32_16x16x32_bf16 v[40:43], v[198:201], v[206:209], v[40:43]
	v_mfma_f32_16x16x32_bf16 v[28:31], v[186:189], v[214:217], v[28:31]
	v_mfma_f32_16x16x32_bf16 v[24:27], v[198:201], v[214:217], v[24:27]
	v_mfma_f32_16x16x32_bf16 v[12:15], v[186:189], v[222:225], v[12:15]
	v_mfma_f32_16x16x32_bf16 v[8:11], v[198:201], v[222:225], v[8:11]
	v_mfma_f32_16x16x32_bf16 v[4:7], v[186:189], v[230:233], v[4:7]
	v_mfma_f32_16x16x32_bf16 v[0:3], v[198:201], v[230:233], v[0:3]
	v_mfma_f32_16x16x32_bf16 v[44:47], v[194:197], v[210:213], v[44:47]
	v_mfma_f32_16x16x32_bf16 v[40:43], v[202:205], v[210:213], v[40:43]
	v_mfma_f32_16x16x32_bf16 v[28:31], v[194:197], v[218:221], v[28:31]
	v_mfma_f32_16x16x32_bf16 v[24:27], v[202:205], v[218:221], v[24:27]
	v_mfma_f32_16x16x32_bf16 v[12:15], v[194:197], v[226:229], v[12:15]
	v_mfma_f32_16x16x32_bf16 v[8:11], v[202:205], v[226:229], v[8:11]
	v_mfma_f32_16x16x32_bf16 v[4:7], v[194:197], v[234:237], v[4:7]
	v_mfma_f32_16x16x32_bf16 v[0:3], v[202:205], v[234:237], v[0:3]
	s_barrier
	s_add_i32 s72, 0, 0x18000
	v_add_u32_e32 v136, s72, v152
	s_add_i32 s73, 0, 0x1c000
	ds_read_b128 v[170:173], v136
	ds_read_b128 v[174:177], v136 offset:1024
	ds_read_b128 v[178:181], v136 offset:2048
	ds_read_b128 v[182:185], v136 offset:3072
	v_add_u32_e32 v136, s73, v152
	ds_read_b128 v[186:189], v136
	ds_read_b128 v[194:197], v136 offset:1024
	ds_read_b128 v[198:201], v136 offset:2048
	ds_read_b128 v[202:205], v136 offset:3072
	s_add_u32 s46, s46, 0x40000
	s_addc_u32 s47, s47, 0
	s_mov_b32 m0, s33
	v_lshl_add_u64 v[242:243], s[46:47], 0, v[134:135]
	ds_read_b128 v[206:209], v166 offset:32768
	ds_read_b128 v[210:213], v166 offset:33792
	ds_read_b128 v[214:217], v166 offset:34816
	ds_read_b128 v[218:221], v166 offset:35840
	ds_read_b128 v[222:225], v166 offset:36864
	ds_read_b128 v[226:229], v166 offset:37888
	ds_read_b128 v[230:233], v166 offset:38912
	ds_read_b128 v[234:237], v166 offset:39936
	global_load_lds_dwordx4 v[242:243], off
	v_lshl_add_u64 v[242:243], s[46:47], 0, v[130:131]
	s_mov_b32 m0, s48
	s_nop 0
	global_load_lds_dwordx4 v[242:243], off
	s_waitcnt vmcnt(8)
	s_waitcnt lgkmcnt(0)
	s_barrier
	s_waitcnt lgkmcnt(0)
	v_mfma_f32_16x16x32_bf16 v[124:127], v[170:173], v[206:209], v[124:127]
	v_mfma_f32_16x16x32_bf16 v[120:123], v[178:181], v[206:209], v[120:123]
	v_mfma_f32_16x16x32_bf16 v[116:119], v[170:173], v[214:217], v[116:119]
	v_mfma_f32_16x16x32_bf16 v[112:115], v[178:181], v[214:217], v[112:115]
	v_mfma_f32_16x16x32_bf16 v[100:103], v[170:173], v[222:225], v[100:103]
	v_mfma_f32_16x16x32_bf16 v[96:99], v[178:181], v[222:225], v[96:99]
	v_mfma_f32_16x16x32_bf16 v[84:87], v[170:173], v[230:233], v[84:87]
	v_mfma_f32_16x16x32_bf16 v[80:83], v[178:181], v[230:233], v[80:83]
	v_mfma_f32_16x16x32_bf16 v[124:127], v[174:177], v[210:213], v[124:127]
	v_mfma_f32_16x16x32_bf16 v[120:123], v[182:185], v[210:213], v[120:123]
	v_mfma_f32_16x16x32_bf16 v[116:119], v[174:177], v[218:221], v[116:119]
	v_mfma_f32_16x16x32_bf16 v[112:115], v[182:185], v[218:221], v[112:115]
	v_mfma_f32_16x16x32_bf16 v[100:103], v[174:177], v[226:229], v[100:103]
	v_mfma_f32_16x16x32_bf16 v[96:99], v[182:185], v[226:229], v[96:99]
	v_mfma_f32_16x16x32_bf16 v[84:87], v[174:177], v[234:237], v[84:87]
	v_mfma_f32_16x16x32_bf16 v[80:83], v[182:185], v[234:237], v[80:83]
	v_mfma_f32_16x16x32_bf16 v[108:111], v[186:189], v[206:209], v[108:111]
	v_mfma_f32_16x16x32_bf16 v[104:107], v[198:201], v[206:209], v[104:107]
	v_mfma_f32_16x16x32_bf16 v[92:95], v[186:189], v[214:217], v[92:95]
	v_mfma_f32_16x16x32_bf16 v[88:91], v[198:201], v[214:217], v[88:91]
	v_mfma_f32_16x16x32_bf16 v[76:79], v[186:189], v[222:225], v[76:79]
	v_mfma_f32_16x16x32_bf16 v[72:75], v[198:201], v[222:225], v[72:75]
	v_mfma_f32_16x16x32_bf16 v[68:71], v[186:189], v[230:233], v[68:71]
	v_mfma_f32_16x16x32_bf16 v[64:67], v[198:201], v[230:233], v[64:67]
	v_mfma_f32_16x16x32_bf16 v[108:111], v[194:197], v[210:213], v[108:111]
	v_mfma_f32_16x16x32_bf16 v[104:107], v[202:205], v[210:213], v[104:107]
	v_mfma_f32_16x16x32_bf16 v[92:95], v[194:197], v[218:221], v[92:95]
	v_mfma_f32_16x16x32_bf16 v[88:91], v[202:205], v[218:221], v[88:91]
	v_mfma_f32_16x16x32_bf16 v[76:79], v[194:197], v[226:229], v[76:79]
	v_mfma_f32_16x16x32_bf16 v[72:75], v[202:205], v[226:229], v[72:75]
	v_mfma_f32_16x16x32_bf16 v[68:71], v[194:197], v[234:237], v[68:71]
	v_mfma_f32_16x16x32_bf16 v[64:67], v[202:205], v[234:237], v[64:67]
	s_barrier
	s_add_i32 s46, s72, s14
	v_lshl_add_u64 v[148:149], v[148:149], 0, s[4:5]
	s_mov_b32 m0, s46
	ds_read_b128 v[206:209], v166 offset:49152
	ds_read_b128 v[210:213], v166 offset:50176
	ds_read_b128 v[214:217], v166 offset:51200
	ds_read_b128 v[218:221], v166 offset:52224
	ds_read_b128 v[222:225], v166 offset:53248
	ds_read_b128 v[226:229], v166 offset:54272
	ds_read_b128 v[230:233], v166 offset:55296
	ds_read_b128 v[234:237], v166 offset:56320
	global_load_lds_dwordx4 v[148:149], off
	s_add_i32 m0, s46, 0x2000
	s_add_u32 s42, s42, 0x40080
	v_lshl_add_u64 v[148:149], v[190:191], 0, s[4:5]
	s_addc_u32 s43, s43, 0
	s_add_i32 s46, s73, s14
	global_load_lds_dwordx4 v[148:149], off
	v_lshl_add_u64 v[148:149], s[42:43], 0, v[132:133]
	s_mov_b32 m0, s46
	s_nop 0
	global_load_lds_dwordx4 v[148:149], off
	v_lshl_add_u64 v[148:149], s[42:43], 0, v[128:129]
	s_add_i32 m0, s46, 0x2000
	s_nop 0
	global_load_lds_dwordx4 v[148:149], off
	v_lshl_add_u64 v[148:149], v[238:239], 0, s[4:5]
	s_mov_b32 m0, s50
	s_nop 0
	global_load_lds_dwordx4 v[148:149], off
	v_lshl_add_u64 v[148:149], v[240:241], 0, s[4:5]
	s_mov_b32 m0, s51
	s_nop 0
	global_load_lds_dwordx4 v[148:149], off
	s_waitcnt vmcnt(8)
	s_waitcnt lgkmcnt(0)
	s_barrier
	s_waitcnt lgkmcnt(0)
	v_mfma_f32_16x16x32_bf16 v[60:63], v[170:173], v[206:209], v[60:63]
	v_mfma_f32_16x16x32_bf16 v[56:59], v[178:181], v[206:209], v[56:59]
	v_mfma_f32_16x16x32_bf16 v[52:55], v[170:173], v[214:217], v[52:55]
	v_mfma_f32_16x16x32_bf16 v[48:51], v[178:181], v[214:217], v[48:51]
	v_mfma_f32_16x16x32_bf16 v[36:39], v[170:173], v[222:225], v[36:39]
	v_mfma_f32_16x16x32_bf16 v[32:35], v[178:181], v[222:225], v[32:35]
	v_mfma_f32_16x16x32_bf16 v[20:23], v[170:173], v[230:233], v[20:23]
	v_mfma_f32_16x16x32_bf16 v[16:19], v[178:181], v[230:233], v[16:19]
	v_mfma_f32_16x16x32_bf16 v[60:63], v[174:177], v[210:213], v[60:63]
	v_mfma_f32_16x16x32_bf16 v[56:59], v[182:185], v[210:213], v[56:59]
	v_mfma_f32_16x16x32_bf16 v[52:55], v[174:177], v[218:221], v[52:55]
	v_mfma_f32_16x16x32_bf16 v[48:51], v[182:185], v[218:221], v[48:51]
	v_mfma_f32_16x16x32_bf16 v[36:39], v[174:177], v[226:229], v[36:39]
	v_mfma_f32_16x16x32_bf16 v[32:35], v[182:185], v[226:229], v[32:35]
	v_mfma_f32_16x16x32_bf16 v[20:23], v[174:177], v[234:237], v[20:23]
	v_mfma_f32_16x16x32_bf16 v[16:19], v[182:185], v[234:237], v[16:19]
	v_mfma_f32_16x16x32_bf16 v[44:47], v[186:189], v[206:209], v[44:47]
	v_mfma_f32_16x16x32_bf16 v[40:43], v[198:201], v[206:209], v[40:43]
	v_mfma_f32_16x16x32_bf16 v[28:31], v[186:189], v[214:217], v[28:31]
	v_mfma_f32_16x16x32_bf16 v[24:27], v[198:201], v[214:217], v[24:27]
	v_mfma_f32_16x16x32_bf16 v[12:15], v[186:189], v[222:225], v[12:15]
	v_mfma_f32_16x16x32_bf16 v[8:11], v[198:201], v[222:225], v[8:11]
	v_mfma_f32_16x16x32_bf16 v[4:7], v[186:189], v[230:233], v[4:7]
	v_mfma_f32_16x16x32_bf16 v[0:3], v[198:201], v[230:233], v[0:3]
	v_mfma_f32_16x16x32_bf16 v[44:47], v[194:197], v[210:213], v[44:47]
	v_mfma_f32_16x16x32_bf16 v[40:43], v[202:205], v[210:213], v[40:43]
	v_mfma_f32_16x16x32_bf16 v[28:31], v[194:197], v[218:221], v[28:31]
	v_mfma_f32_16x16x32_bf16 v[24:27], v[202:205], v[218:221], v[24:27]
	v_mfma_f32_16x16x32_bf16 v[12:15], v[194:197], v[226:229], v[12:15]
	v_mfma_f32_16x16x32_bf16 v[8:11], v[202:205], v[226:229], v[8:11]
	v_mfma_f32_16x16x32_bf16 v[4:7], v[194:197], v[234:237], v[4:7]
	v_mfma_f32_16x16x32_bf16 v[0:3], v[202:205], v[234:237], v[0:3]
	s_barrier
	s_add_i32 s71, s71, 2
	s_add_u32 s36, s36, 0x100
	s_addc_u32 s37, s37, 0
	s_add_u32 s69, s69, 0x100
	s_addc_u32 s70, s70, 0
	s_cmp_gt_u32 s71, 13
	s_cbranch_scc0 .LBB0_640
	s_and_b64 vcc, exec, s[6:7]
	s_cbranch_vccz .LBB0_643
	s_barrier

.LBB0_677:
	ds_read_b128 v[150:153], v147
	ds_read_b128 v[154:157], v147 offset:1024
	ds_read_b128 v[158:161], v147 offset:2048
	ds_read_b128 v[162:165], v147 offset:3072
	ds_read_b128 v[166:169], v148
	ds_read_b128 v[170:173], v148 offset:1024
	ds_read_b128 v[174:177], v148 offset:2048
	ds_read_b128 v[178:181], v148 offset:3072
	s_add_u32 s42, s36, 0xfffc0080
	s_addc_u32 s43, s37, -1
	s_cmp_eq_u32 s67, 12
	s_cselect_b32 s47, s13, s43
	s_cselect_b32 s46, s53, s42
	s_cselect_b32 s43, s11, s66
	s_cselect_b32 s42, s64, s65
	v_lshl_add_u64 v[190:191], s[36:37], 0, v[136:137]
	s_add_i32 m0, s21, 0xc000
	ds_read_b128 v[182:185], v149
	ds_read_b128 v[186:189], v149 offset:1024
	ds_read_b128 v[194:197], v149 offset:2048
	ds_read_b128 v[198:201], v149 offset:3072
	ds_read_b128 v[202:205], v149 offset:4096
	ds_read_b128 v[206:209], v149 offset:5120
	ds_read_b128 v[210:213], v149 offset:6144
	ds_read_b128 v[214:217], v149 offset:7168
	global_load_lds_dwordx4 v[190:191], off
	v_lshl_add_u64 v[190:191], s[36:37], 0, v[138:139]
	s_add_i32 m0, s21, 0xe000
	s_nop 0
	global_load_lds_dwordx4 v[190:191], off
	s_waitcnt vmcnt(8)
	s_waitcnt lgkmcnt(0)
	s_barrier
	s_waitcnt lgkmcnt(0)
	v_mfma_f32_16x16x32_bf16 v[124:127], v[150:153], v[182:185], v[124:127]
	v_mfma_f32_16x16x32_bf16 v[120:123], v[158:161], v[182:185], v[120:123]
	v_mfma_f32_16x16x32_bf16 v[116:119], v[150:153], v[194:197], v[116:119]
	v_mfma_f32_16x16x32_bf16 v[112:115], v[158:161], v[194:197], v[112:115]
	v_mfma_f32_16x16x32_bf16 v[100:103], v[150:153], v[202:205], v[100:103]
	v_mfma_f32_16x16x32_bf16 v[96:99], v[158:161], v[202:205], v[96:99]
	v_mfma_f32_16x16x32_bf16 v[84:87], v[150:153], v[210:213], v[84:87]
	v_mfma_f32_16x16x32_bf16 v[80:83], v[158:161], v[210:213], v[80:83]
	v_mfma_f32_16x16x32_bf16 v[124:127], v[154:157], v[186:189], v[124:127]
	v_mfma_f32_16x16x32_bf16 v[120:123], v[162:165], v[186:189], v[120:123]
	v_mfma_f32_16x16x32_bf16 v[116:119], v[154:157], v[198:201], v[116:119]
	v_mfma_f32_16x16x32_bf16 v[112:115], v[162:165], v[198:201], v[112:115]
	v_mfma_f32_16x16x32_bf16 v[100:103], v[154:157], v[206:209], v[100:103]
	v_mfma_f32_16x16x32_bf16 v[96:99], v[162:165], v[206:209], v[96:99]
	v_mfma_f32_16x16x32_bf16 v[84:87], v[154:157], v[214:217], v[84:87]
	v_mfma_f32_16x16x32_bf16 v[80:83], v[162:165], v[214:217], v[80:83]
	v_mfma_f32_16x16x32_bf16 v[108:111], v[166:169], v[182:185], v[108:111]
	v_mfma_f32_16x16x32_bf16 v[104:107], v[174:177], v[182:185], v[104:107]
	v_mfma_f32_16x16x32_bf16 v[92:95], v[166:169], v[194:197], v[92:95]
	v_mfma_f32_16x16x32_bf16 v[88:91], v[174:177], v[194:197], v[88:91]
	v_mfma_f32_16x16x32_bf16 v[76:79], v[166:169], v[202:205], v[76:79]
	v_mfma_f32_16x16x32_bf16 v[72:75], v[174:177], v[202:205], v[72:75]
	v_mfma_f32_16x16x32_bf16 v[68:71], v[166:169], v[210:213], v[68:71]
	v_mfma_f32_16x16x32_bf16 v[64:67], v[174:177], v[210:213], v[64:67]
	v_mfma_f32_16x16x32_bf16 v[108:111], v[170:173], v[186:189], v[108:111]
	v_mfma_f32_16x16x32_bf16 v[104:107], v[178:181], v[186:189], v[104:107]
	v_mfma_f32_16x16x32_bf16 v[92:95], v[170:173], v[198:201], v[92:95]
	v_mfma_f32_16x16x32_bf16 v[88:91], v[178:181], v[198:201], v[88:91]
	v_mfma_f32_16x16x32_bf16 v[76:79], v[170:173], v[206:209], v[76:79]
	v_mfma_f32_16x16x32_bf16 v[72:75], v[178:181], v[206:209], v[72:75]
	v_mfma_f32_16x16x32_bf16 v[68:71], v[170:173], v[214:217], v[68:71]
	v_mfma_f32_16x16x32_bf16 v[64:67], v[178:181], v[214:217], v[64:67]
	s_barrier
	s_add_i32 s68, s51, s14
	v_lshl_add_u64 v[190:191], s[42:43], 0, v[132:133]
	s_mov_b32 m0, s68
	ds_read_b128 v[182:185], v149 offset:16384
	ds_read_b128 v[186:189], v149 offset:17408
	ds_read_b128 v[194:197], v149 offset:18432
	ds_read_b128 v[198:201], v149 offset:19456
	ds_read_b128 v[202:205], v149 offset:20480
	ds_read_b128 v[206:209], v149 offset:21504
	ds_read_b128 v[210:213], v149 offset:22528
	ds_read_b128 v[214:217], v149 offset:23552
	global_load_lds_dwordx4 v[190:191], off
	s_add_i32 m0, s68, 0x2000
	s_add_u32 s68, s42, 0x40000
	v_lshl_add_u64 v[218:219], s[42:43], 0, v[128:129]
	s_addc_u32 s69, s43, 0
	s_add_i32 s70, s52, s14
	global_load_lds_dwordx4 v[218:219], off
	v_lshl_add_u64 v[220:221], s[68:69], 0, v[132:133]
	s_mov_b32 m0, s70
	v_lshl_add_u64 v[222:223], s[46:47], 0, v[130:131]
	global_load_lds_dwordx4 v[220:221], off
	v_lshl_add_u64 v[220:221], s[68:69], 0, v[128:129]
	s_add_i32 m0, s70, 0x2000
	s_nop 0
	global_load_lds_dwordx4 v[220:221], off
	v_lshl_add_u64 v[220:221], s[46:47], 0, v[134:135]
	s_mov_b32 m0, s21
	s_nop 0
	global_load_lds_dwordx4 v[220:221], off
	s_mov_b32 m0, s22
	s_nop 0
	global_load_lds_dwordx4 v[222:223], off
	s_waitcnt vmcnt(8)
	s_waitcnt lgkmcnt(0)
	s_barrier
	s_waitcnt lgkmcnt(0)
	v_mfma_f32_16x16x32_bf16 v[60:63], v[150:153], v[182:185], v[60:63]
	v_mfma_f32_16x16x32_bf16 v[56:59], v[158:161], v[182:185], v[56:59]
	v_mfma_f32_16x16x32_bf16 v[52:55], v[150:153], v[194:197], v[52:55]
	v_mfma_f32_16x16x32_bf16 v[48:51], v[158:161], v[194:197], v[48:51]
	v_mfma_f32_16x16x32_bf16 v[36:39], v[150:153], v[202:205], v[36:39]
	v_mfma_f32_16x16x32_bf16 v[32:35], v[158:161], v[202:205], v[32:35]
	v_mfma_f32_16x16x32_bf16 v[20:23], v[150:153], v[210:213], v[20:23]
	v_mfma_f32_16x16x32_bf16 v[16:19], v[158:161], v[210:213], v[16:19]
	v_mfma_f32_16x16x32_bf16 v[60:63], v[154:157], v[186:189], v[60:63]
	v_mfma_f32_16x16x32_bf16 v[56:59], v[162:165], v[186:189], v[56:59]
	v_mfma_f32_16x16x32_bf16 v[52:55], v[154:157], v[198:201], v[52:55]
	v_mfma_f32_16x16x32_bf16 v[48:51], v[162:165], v[198:201], v[48:51]
	v_mfma_f32_16x16x32_bf16 v[36:39], v[154:157], v[206:209], v[36:39]
	v_mfma_f32_16x16x32_bf16 v[32:35], v[162:165], v[206:209], v[32:35]
	v_mfma_f32_16x16x32_bf16 v[20:23], v[154:157], v[214:217], v[20:23]
	v_mfma_f32_16x16x32_bf16 v[16:19], v[162:165], v[214:217], v[16:19]
	v_mfma_f32_16x16x32_bf16 v[44:47], v[166:169], v[182:185], v[44:47]
	v_mfma_f32_16x16x32_bf16 v[40:43], v[174:177], v[182:185], v[40:43]
	v_mfma_f32_16x16x32_bf16 v[28:31], v[166:169], v[194:197], v[28:31]
	v_mfma_f32_16x16x32_bf16 v[24:27], v[174:177], v[194:197], v[24:27]
	v_mfma_f32_16x16x32_bf16 v[12:15], v[166:169], v[202:205], v[12:15]
	v_mfma_f32_16x16x32_bf16 v[8:11], v[174:177], v[202:205], v[8:11]
	v_mfma_f32_16x16x32_bf16 v[4:7], v[166:169], v[210:213], v[4:7]
	v_mfma_f32_16x16x32_bf16 v[0:3], v[174:177], v[210:213], v[0:3]
	v_mfma_f32_16x16x32_bf16 v[44:47], v[170:173], v[186:189], v[44:47]
	v_mfma_f32_16x16x32_bf16 v[40:43], v[178:181], v[186:189], v[40:43]
	v_mfma_f32_16x16x32_bf16 v[28:31], v[170:173], v[198:201], v[28:31]
	v_mfma_f32_16x16x32_bf16 v[24:27], v[178:181], v[198:201], v[24:27]
	v_mfma_f32_16x16x32_bf16 v[12:15], v[170:173], v[206:209], v[12:15]
	v_mfma_f32_16x16x32_bf16 v[8:11], v[178:181], v[206:209], v[8:11]
	v_mfma_f32_16x16x32_bf16 v[4:7], v[170:173], v[214:217], v[4:7]
	v_mfma_f32_16x16x32_bf16 v[0:3], v[178:181], v[214:217], v[0:3]
	s_barrier
	s_add_i32 s68, 0, 0x18000
	s_add_i32 s69, 0, 0x1c000
	v_add_u32_e32 v162, s68, v145
	v_add_u32_e32 v178, s69, v145
	ds_read_b128 v[150:153], v162
	ds_read_b128 v[154:157], v162 offset:1024
	ds_read_b128 v[158:161], v162 offset:2048
	ds_read_b128 v[162:165], v162 offset:3072
	ds_read_b128 v[166:169], v178
	ds_read_b128 v[170:173], v178 offset:1024
	ds_read_b128 v[174:177], v178 offset:2048
	ds_read_b128 v[178:181], v178 offset:3072
	s_add_u32 s46, s46, 0x40000
	s_addc_u32 s47, s47, 0
	s_mov_b32 m0, s23
	v_lshl_add_u64 v[224:225], s[46:47], 0, v[134:135]
	ds_read_b128 v[182:185], v149 offset:32768
	ds_read_b128 v[186:189], v149 offset:33792
	ds_read_b128 v[194:197], v149 offset:34816
	ds_read_b128 v[198:201], v149 offset:35840
	ds_read_b128 v[202:205], v149 offset:36864
	ds_read_b128 v[206:209], v149 offset:37888
	ds_read_b128 v[210:213], v149 offset:38912
	ds_read_b128 v[214:217], v149 offset:39936
	global_load_lds_dwordx4 v[224:225], off
	v_lshl_add_u64 v[224:225], s[46:47], 0, v[130:131]
	s_mov_b32 m0, s33
	s_nop 0
	global_load_lds_dwordx4 v[224:225], off
	s_waitcnt vmcnt(8)
	s_waitcnt lgkmcnt(0)
	s_barrier
	s_waitcnt lgkmcnt(0)
	v_mfma_f32_16x16x32_bf16 v[124:127], v[150:153], v[182:185], v[124:127]
	v_mfma_f32_16x16x32_bf16 v[120:123], v[158:161], v[182:185], v[120:123]
	v_mfma_f32_16x16x32_bf16 v[116:119], v[150:153], v[194:197], v[116:119]
	v_mfma_f32_16x16x32_bf16 v[112:115], v[158:161], v[194:197], v[112:115]
	v_mfma_f32_16x16x32_bf16 v[100:103], v[150:153], v[202:205], v[100:103]
	v_mfma_f32_16x16x32_bf16 v[96:99], v[158:161], v[202:205], v[96:99]
	v_mfma_f32_16x16x32_bf16 v[84:87], v[150:153], v[210:213], v[84:87]
	v_mfma_f32_16x16x32_bf16 v[80:83], v[158:161], v[210:213], v[80:83]
	v_mfma_f32_16x16x32_bf16 v[124:127], v[154:157], v[186:189], v[124:127]
	v_mfma_f32_16x16x32_bf16 v[120:123], v[162:165], v[186:189], v[120:123]
	v_mfma_f32_16x16x32_bf16 v[116:119], v[154:157], v[198:201], v[116:119]
	v_mfma_f32_16x16x32_bf16 v[112:115], v[162:165], v[198:201], v[112:115]
	v_mfma_f32_16x16x32_bf16 v[100:103], v[154:157], v[206:209], v[100:103]
	v_mfma_f32_16x16x32_bf16 v[96:99], v[162:165], v[206:209], v[96:99]
	v_mfma_f32_16x16x32_bf16 v[84:87], v[154:157], v[214:217], v[84:87]
	v_mfma_f32_16x16x32_bf16 v[80:83], v[162:165], v[214:217], v[80:83]
	v_mfma_f32_16x16x32_bf16 v[108:111], v[166:169], v[182:185], v[108:111]
	v_mfma_f32_16x16x32_bf16 v[104:107], v[174:177], v[182:185], v[104:107]
	v_mfma_f32_16x16x32_bf16 v[92:95], v[166:169], v[194:197], v[92:95]
	v_mfma_f32_16x16x32_bf16 v[88:91], v[174:177], v[194:197], v[88:91]
	v_mfma_f32_16x16x32_bf16 v[76:79], v[166:169], v[202:205], v[76:79]
	v_mfma_f32_16x16x32_bf16 v[72:75], v[174:177], v[202:205], v[72:75]
	v_mfma_f32_16x16x32_bf16 v[68:71], v[166:169], v[210:213], v[68:71]
	v_mfma_f32_16x16x32_bf16 v[64:67], v[174:177], v[210:213], v[64:67]
	v_mfma_f32_16x16x32_bf16 v[108:111], v[170:173], v[186:189], v[108:111]
	v_mfma_f32_16x16x32_bf16 v[104:107], v[178:181], v[186:189], v[104:107]
	v_mfma_f32_16x16x32_bf16 v[92:95], v[170:173], v[198:201], v[92:95]
	v_mfma_f32_16x16x32_bf16 v[88:91], v[178:181], v[198:201], v[88:91]
	v_mfma_f32_16x16x32_bf16 v[76:79], v[170:173], v[206:209], v[76:79]
	v_mfma_f32_16x16x32_bf16 v[72:75], v[178:181], v[206:209], v[72:75]
	v_mfma_f32_16x16x32_bf16 v[68:71], v[170:173], v[214:217], v[68:71]
	v_mfma_f32_16x16x32_bf16 v[64:67], v[178:181], v[214:217], v[64:67]
	s_barrier
	s_add_i32 s46, s68, s14
	v_lshl_add_u64 v[190:191], v[190:191], 0, s[4:5]
	s_mov_b32 m0, s46
	ds_read_b128 v[182:185], v149 offset:49152
	ds_read_b128 v[186:189], v149 offset:50176
	ds_read_b128 v[194:197], v149 offset:51200
	ds_read_b128 v[198:201], v149 offset:52224
	ds_read_b128 v[202:205], v149 offset:53248
	ds_read_b128 v[206:209], v149 offset:54272
	ds_read_b128 v[210:213], v149 offset:55296
	ds_read_b128 v[214:217], v149 offset:56320
	global_load_lds_dwordx4 v[190:191], off
	s_add_i32 m0, s46, 0x2000
	s_add_u32 s42, s42, 0x40080
	v_lshl_add_u64 v[190:191], v[218:219], 0, s[4:5]
	s_addc_u32 s43, s43, 0
	s_add_i32 s46, s69, s14
	global_load_lds_dwordx4 v[190:191], off
	v_lshl_add_u64 v[190:191], s[42:43], 0, v[132:133]
	s_mov_b32 m0, s46
	s_nop 0
	global_load_lds_dwordx4 v[190:191], off
	v_lshl_add_u64 v[190:191], s[42:43], 0, v[128:129]
	s_add_i32 m0, s46, 0x2000
	s_nop 0
	global_load_lds_dwordx4 v[190:191], off
	v_lshl_add_u64 v[190:191], v[220:221], 0, s[4:5]
	s_mov_b32 m0, s49
	s_nop 0
	global_load_lds_dwordx4 v[190:191], off
	v_lshl_add_u64 v[190:191], v[222:223], 0, s[4:5]
	s_mov_b32 m0, s50
	s_nop 0
	global_load_lds_dwordx4 v[190:191], off
	s_waitcnt vmcnt(8)
	s_waitcnt lgkmcnt(0)
	s_barrier
	s_waitcnt lgkmcnt(0)
	v_mfma_f32_16x16x32_bf16 v[60:63], v[150:153], v[182:185], v[60:63]
	v_mfma_f32_16x16x32_bf16 v[56:59], v[158:161], v[182:185], v[56:59]
	v_mfma_f32_16x16x32_bf16 v[52:55], v[150:153], v[194:197], v[52:55]
	v_mfma_f32_16x16x32_bf16 v[48:51], v[158:161], v[194:197], v[48:51]
	v_mfma_f32_16x16x32_bf16 v[36:39], v[150:153], v[202:205], v[36:39]
	v_mfma_f32_16x16x32_bf16 v[32:35], v[158:161], v[202:205], v[32:35]
	v_mfma_f32_16x16x32_bf16 v[20:23], v[150:153], v[210:213], v[20:23]
	v_mfma_f32_16x16x32_bf16 v[16:19], v[158:161], v[210:213], v[16:19]
	v_mfma_f32_16x16x32_bf16 v[60:63], v[154:157], v[186:189], v[60:63]
	v_mfma_f32_16x16x32_bf16 v[56:59], v[162:165], v[186:189], v[56:59]
	v_mfma_f32_16x16x32_bf16 v[52:55], v[154:157], v[198:201], v[52:55]
	v_mfma_f32_16x16x32_bf16 v[48:51], v[162:165], v[198:201], v[48:51]
	v_mfma_f32_16x16x32_bf16 v[36:39], v[154:157], v[206:209], v[36:39]
	v_mfma_f32_16x16x32_bf16 v[32:35], v[162:165], v[206:209], v[32:35]
	v_mfma_f32_16x16x32_bf16 v[20:23], v[154:157], v[214:217], v[20:23]
	v_mfma_f32_16x16x32_bf16 v[16:19], v[162:165], v[214:217], v[16:19]
	v_mfma_f32_16x16x32_bf16 v[44:47], v[166:169], v[182:185], v[44:47]
	v_mfma_f32_16x16x32_bf16 v[40:43], v[174:177], v[182:185], v[40:43]
	v_mfma_f32_16x16x32_bf16 v[28:31], v[166:169], v[194:197], v[28:31]
	v_mfma_f32_16x16x32_bf16 v[24:27], v[174:177], v[194:197], v[24:27]
	v_mfma_f32_16x16x32_bf16 v[12:15], v[166:169], v[202:205], v[12:15]
	v_mfma_f32_16x16x32_bf16 v[8:11], v[174:177], v[202:205], v[8:11]
	v_mfma_f32_16x16x32_bf16 v[4:7], v[166:169], v[210:213], v[4:7]
	v_mfma_f32_16x16x32_bf16 v[0:3], v[174:177], v[210:213], v[0:3]
	v_mfma_f32_16x16x32_bf16 v[44:47], v[170:173], v[186:189], v[44:47]
	v_mfma_f32_16x16x32_bf16 v[40:43], v[178:181], v[186:189], v[40:43]
	v_mfma_f32_16x16x32_bf16 v[28:31], v[170:173], v[198:201], v[28:31]
	v_mfma_f32_16x16x32_bf16 v[24:27], v[178:181], v[198:201], v[24:27]
	v_mfma_f32_16x16x32_bf16 v[12:15], v[170:173], v[206:209], v[12:15]
	v_mfma_f32_16x16x32_bf16 v[8:11], v[178:181], v[206:209], v[8:11]
	v_mfma_f32_16x16x32_bf16 v[4:7], v[170:173], v[214:217], v[4:7]
	v_mfma_f32_16x16x32_bf16 v[0:3], v[178:181], v[214:217], v[0:3]
	s_barrier
	s_add_i32 s67, s67, 2
	s_add_u32 s36, s36, 0x100
	s_addc_u32 s37, s37, 0
	s_add_u32 s65, s65, 0x100
	s_addc_u32 s66, s66, 0
	s_cmp_gt_u32 s67, 13
	s_cbranch_scc0 .LBB0_677
	s_and_b64 vcc, exec, s[6:7]
	s_cbranch_vccz .LBB0_680
	s_barrier

.LBB0_885:
	ds_read_b128 v[140:143], v149
	ds_read_b128 v[152:155], v149 offset:1024
	ds_read_b128 v[156:159], v149 offset:2048
	ds_read_b128 v[160:163], v149 offset:3072
	ds_read_b128 v[164:167], v150
	ds_read_b128 v[168:171], v150 offset:1024
	ds_read_b128 v[172:175], v150 offset:2048
	ds_read_b128 v[176:179], v150 offset:3072
	s_add_u32 s34, s30, 0xfffc0080
	s_addc_u32 s35, s31, -1
	s_cmp_eq_u32 s53, 12
	s_cselect_b32 s37, s17, s35
	s_cselect_b32 s36, s27, s34
	s_cselect_b32 s35, s13, s52
	s_cselect_b32 s34, s50, s51
	v_lshl_add_u64 v[214:215], s[30:31], 0, v[132:133]
	s_add_i32 m0, s15, 0xc000
	ds_read_b128 v[180:183], v151
	ds_read_b128 v[184:187], v151 offset:1024
	ds_read_b128 v[188:191], v151 offset:2048
	ds_read_b128 v[194:197], v151 offset:3072
	ds_read_b128 v[198:201], v151 offset:4096
	ds_read_b128 v[202:205], v151 offset:5120
	ds_read_b128 v[206:209], v151 offset:6144
	ds_read_b128 v[210:213], v151 offset:7168
	global_load_lds_dwordx4 v[214:215], off
	v_lshl_add_u64 v[214:215], s[30:31], 0, v[134:135]
	s_add_i32 m0, s15, 0xe000
	s_nop 0
	global_load_lds_dwordx4 v[214:215], off
	s_waitcnt vmcnt(8)
	s_waitcnt lgkmcnt(0)
	s_barrier
	s_waitcnt lgkmcnt(0)
	v_mfma_f32_16x16x32_bf16 v[124:127], v[140:143], v[180:183], v[124:127]
	v_mfma_f32_16x16x32_bf16 v[120:123], v[156:159], v[180:183], v[120:123]
	v_mfma_f32_16x16x32_bf16 v[108:111], v[140:143], v[188:191], v[108:111]
	v_mfma_f32_16x16x32_bf16 v[104:107], v[156:159], v[188:191], v[104:107]
	v_mfma_f32_16x16x32_bf16 v[92:95], v[140:143], v[198:201], v[92:95]
	v_mfma_f32_16x16x32_bf16 v[88:91], v[156:159], v[198:201], v[88:91]
	v_mfma_f32_16x16x32_bf16 v[76:79], v[140:143], v[206:209], v[76:79]
	v_mfma_f32_16x16x32_bf16 v[72:75], v[156:159], v[206:209], v[72:75]
	v_mfma_f32_16x16x32_bf16 v[124:127], v[152:155], v[184:187], v[124:127]
	v_mfma_f32_16x16x32_bf16 v[120:123], v[160:163], v[184:187], v[120:123]
	v_mfma_f32_16x16x32_bf16 v[108:111], v[152:155], v[194:197], v[108:111]
	v_mfma_f32_16x16x32_bf16 v[104:107], v[160:163], v[194:197], v[104:107]
	v_mfma_f32_16x16x32_bf16 v[92:95], v[152:155], v[202:205], v[92:95]
	v_mfma_f32_16x16x32_bf16 v[88:91], v[160:163], v[202:205], v[88:91]
	v_mfma_f32_16x16x32_bf16 v[76:79], v[152:155], v[210:213], v[76:79]
	v_mfma_f32_16x16x32_bf16 v[72:75], v[160:163], v[210:213], v[72:75]
	v_mfma_f32_16x16x32_bf16 v[116:119], v[164:167], v[180:183], v[116:119]
	v_mfma_f32_16x16x32_bf16 v[112:115], v[172:175], v[180:183], v[112:115]
	v_mfma_f32_16x16x32_bf16 v[100:103], v[164:167], v[188:191], v[100:103]
	v_mfma_f32_16x16x32_bf16 v[96:99], v[172:175], v[188:191], v[96:99]
	v_mfma_f32_16x16x32_bf16 v[84:87], v[164:167], v[198:201], v[84:87]
	v_mfma_f32_16x16x32_bf16 v[80:83], v[172:175], v[198:201], v[80:83]
	v_mfma_f32_16x16x32_bf16 v[68:71], v[164:167], v[206:209], v[68:71]
	v_mfma_f32_16x16x32_bf16 v[64:67], v[172:175], v[206:209], v[64:67]
	v_mfma_f32_16x16x32_bf16 v[116:119], v[168:171], v[184:187], v[116:119]
	v_mfma_f32_16x16x32_bf16 v[112:115], v[176:179], v[184:187], v[112:115]
	v_mfma_f32_16x16x32_bf16 v[100:103], v[168:171], v[194:197], v[100:103]
	v_mfma_f32_16x16x32_bf16 v[96:99], v[176:179], v[194:197], v[96:99]
	v_mfma_f32_16x16x32_bf16 v[84:87], v[168:171], v[202:205], v[84:87]
	v_mfma_f32_16x16x32_bf16 v[80:83], v[176:179], v[202:205], v[80:83]
	v_mfma_f32_16x16x32_bf16 v[68:71], v[168:171], v[210:213], v[68:71]
	v_mfma_f32_16x16x32_bf16 v[64:67], v[176:179], v[210:213], v[64:67]
	s_barrier
	s_add_i32 s54, s47, s14
	v_lshl_add_u64 v[214:215], s[34:35], 0, v[128:129]
	s_mov_b32 m0, s54
	ds_read_b128 v[180:183], v151 offset:16384
	ds_read_b128 v[184:187], v151 offset:17408
	ds_read_b128 v[188:191], v151 offset:18432
	ds_read_b128 v[194:197], v151 offset:19456
	ds_read_b128 v[198:201], v151 offset:20480
	ds_read_b128 v[202:205], v151 offset:21504
	ds_read_b128 v[206:209], v151 offset:22528
	ds_read_b128 v[210:213], v151 offset:23552
	global_load_lds_dwordx4 v[214:215], off
	s_add_i32 m0, s54, 0x2000
	s_add_u32 s54, s34, 0x40000
	v_lshl_add_u64 v[216:217], s[34:35], 0, v[130:131]
	s_addc_u32 s55, s35, 0
	s_add_i32 s56, s48, s14
	global_load_lds_dwordx4 v[216:217], off
	v_lshl_add_u64 v[218:219], s[54:55], 0, v[128:129]
	s_mov_b32 m0, s56
	v_lshl_add_u64 v[220:221], s[36:37], 0, v[130:131]
	global_load_lds_dwordx4 v[218:219], off
	v_lshl_add_u64 v[218:219], s[54:55], 0, v[130:131]
	s_add_i32 m0, s56, 0x2000
	s_nop 0
	global_load_lds_dwordx4 v[218:219], off
	v_lshl_add_u64 v[218:219], s[36:37], 0, v[128:129]
	s_mov_b32 m0, s15
	s_nop 0
	global_load_lds_dwordx4 v[218:219], off
	s_mov_b32 m0, s20
	s_nop 0
	global_load_lds_dwordx4 v[220:221], off
	s_waitcnt vmcnt(8)
	s_waitcnt lgkmcnt(0)
	s_barrier
	s_waitcnt lgkmcnt(0)
	v_mfma_f32_16x16x32_bf16 v[60:63], v[140:143], v[180:183], v[60:63]
	v_mfma_f32_16x16x32_bf16 v[56:59], v[156:159], v[180:183], v[56:59]
	v_mfma_f32_16x16x32_bf16 v[44:47], v[140:143], v[188:191], v[44:47]
	v_mfma_f32_16x16x32_bf16 v[40:43], v[156:159], v[188:191], v[40:43]
	v_mfma_f32_16x16x32_bf16 v[28:31], v[140:143], v[198:201], v[28:31]
	v_mfma_f32_16x16x32_bf16 v[24:27], v[156:159], v[198:201], v[24:27]
	v_mfma_f32_16x16x32_bf16 v[12:15], v[140:143], v[206:209], v[12:15]
	v_mfma_f32_16x16x32_bf16 v[8:11], v[156:159], v[206:209], v[8:11]
	v_mfma_f32_16x16x32_bf16 v[60:63], v[152:155], v[184:187], v[60:63]
	v_mfma_f32_16x16x32_bf16 v[56:59], v[160:163], v[184:187], v[56:59]
	v_mfma_f32_16x16x32_bf16 v[44:47], v[152:155], v[194:197], v[44:47]
	v_mfma_f32_16x16x32_bf16 v[40:43], v[160:163], v[194:197], v[40:43]
	v_mfma_f32_16x16x32_bf16 v[28:31], v[152:155], v[202:205], v[28:31]
	v_mfma_f32_16x16x32_bf16 v[24:27], v[160:163], v[202:205], v[24:27]
	v_mfma_f32_16x16x32_bf16 v[12:15], v[152:155], v[210:213], v[12:15]
	v_mfma_f32_16x16x32_bf16 v[8:11], v[160:163], v[210:213], v[8:11]
	v_mfma_f32_16x16x32_bf16 v[52:55], v[164:167], v[180:183], v[52:55]
	v_mfma_f32_16x16x32_bf16 v[48:51], v[172:175], v[180:183], v[48:51]
	v_mfma_f32_16x16x32_bf16 v[36:39], v[164:167], v[188:191], v[36:39]
	v_mfma_f32_16x16x32_bf16 v[32:35], v[172:175], v[188:191], v[32:35]
	v_mfma_f32_16x16x32_bf16 v[20:23], v[164:167], v[198:201], v[20:23]
	v_mfma_f32_16x16x32_bf16 v[16:19], v[172:175], v[198:201], v[16:19]
	v_mfma_f32_16x16x32_bf16 v[4:7], v[164:167], v[206:209], v[4:7]
	v_mfma_f32_16x16x32_bf16 v[0:3], v[172:175], v[206:209], v[0:3]
	v_mfma_f32_16x16x32_bf16 v[52:55], v[168:171], v[184:187], v[52:55]
	v_mfma_f32_16x16x32_bf16 v[48:51], v[176:179], v[184:187], v[48:51]
	v_mfma_f32_16x16x32_bf16 v[36:39], v[168:171], v[194:197], v[36:39]
	v_mfma_f32_16x16x32_bf16 v[32:35], v[176:179], v[194:197], v[32:35]
	v_mfma_f32_16x16x32_bf16 v[20:23], v[168:171], v[202:205], v[20:23]
	v_mfma_f32_16x16x32_bf16 v[16:19], v[176:179], v[202:205], v[16:19]
	v_mfma_f32_16x16x32_bf16 v[4:7], v[168:171], v[210:213], v[4:7]
	v_mfma_f32_16x16x32_bf16 v[0:3], v[176:179], v[210:213], v[0:3]
	s_barrier
	s_add_i32 s54, 0, 0x18000
	s_add_i32 s55, 0, 0x1c000
	v_add_u32_e32 v160, s54, v145
	v_add_u32_e32 v176, s55, v145
	ds_read_b128 v[140:143], v160
	ds_read_b128 v[152:155], v160 offset:1024
	ds_read_b128 v[156:159], v160 offset:2048
	ds_read_b128 v[160:163], v160 offset:3072
	ds_read_b128 v[164:167], v176
	ds_read_b128 v[168:171], v176 offset:1024
	ds_read_b128 v[172:175], v176 offset:2048
	ds_read_b128 v[176:179], v176 offset:3072
	s_add_u32 s36, s36, 0x40000
	s_addc_u32 s37, s37, 0
	s_mov_b32 m0, s21
	v_lshl_add_u64 v[222:223], s[36:37], 0, v[128:129]
	ds_read_b128 v[180:183], v151 offset:32768
	ds_read_b128 v[184:187], v151 offset:33792
	ds_read_b128 v[188:191], v151 offset:34816
	ds_read_b128 v[194:197], v151 offset:35840
	ds_read_b128 v[198:201], v151 offset:36864
	ds_read_b128 v[202:205], v151 offset:37888
	ds_read_b128 v[206:209], v151 offset:38912
	ds_read_b128 v[210:213], v151 offset:39936
	global_load_lds_dwordx4 v[222:223], off
	v_lshl_add_u64 v[222:223], s[36:37], 0, v[130:131]
	s_mov_b32 m0, s33
	s_nop 0
	global_load_lds_dwordx4 v[222:223], off
	s_waitcnt vmcnt(8)
	s_waitcnt lgkmcnt(0)
	s_barrier
	s_waitcnt lgkmcnt(0)
	v_mfma_f32_16x16x32_bf16 v[124:127], v[140:143], v[180:183], v[124:127]
	v_mfma_f32_16x16x32_bf16 v[120:123], v[156:159], v[180:183], v[120:123]
	v_mfma_f32_16x16x32_bf16 v[108:111], v[140:143], v[188:191], v[108:111]
	v_mfma_f32_16x16x32_bf16 v[104:107], v[156:159], v[188:191], v[104:107]
	v_mfma_f32_16x16x32_bf16 v[92:95], v[140:143], v[198:201], v[92:95]
	v_mfma_f32_16x16x32_bf16 v[88:91], v[156:159], v[198:201], v[88:91]
	v_mfma_f32_16x16x32_bf16 v[76:79], v[140:143], v[206:209], v[76:79]
	v_mfma_f32_16x16x32_bf16 v[72:75], v[156:159], v[206:209], v[72:75]
	v_mfma_f32_16x16x32_bf16 v[124:127], v[152:155], v[184:187], v[124:127]
	v_mfma_f32_16x16x32_bf16 v[120:123], v[160:163], v[184:187], v[120:123]
	v_mfma_f32_16x16x32_bf16 v[108:111], v[152:155], v[194:197], v[108:111]
	v_mfma_f32_16x16x32_bf16 v[104:107], v[160:163], v[194:197], v[104:107]
	v_mfma_f32_16x16x32_bf16 v[92:95], v[152:155], v[202:205], v[92:95]
	v_mfma_f32_16x16x32_bf16 v[88:91], v[160:163], v[202:205], v[88:91]
	v_mfma_f32_16x16x32_bf16 v[76:79], v[152:155], v[210:213], v[76:79]
	v_mfma_f32_16x16x32_bf16 v[72:75], v[160:163], v[210:213], v[72:75]
	v_mfma_f32_16x16x32_bf16 v[116:119], v[164:167], v[180:183], v[116:119]
	v_mfma_f32_16x16x32_bf16 v[112:115], v[172:175], v[180:183], v[112:115]
	v_mfma_f32_16x16x32_bf16 v[100:103], v[164:167], v[188:191], v[100:103]
	v_mfma_f32_16x16x32_bf16 v[96:99], v[172:175], v[188:191], v[96:99]
	v_mfma_f32_16x16x32_bf16 v[84:87], v[164:167], v[198:201], v[84:87]
	v_mfma_f32_16x16x32_bf16 v[80:83], v[172:175], v[198:201], v[80:83]
	v_mfma_f32_16x16x32_bf16 v[68:71], v[164:167], v[206:209], v[68:71]
	v_mfma_f32_16x16x32_bf16 v[64:67], v[172:175], v[206:209], v[64:67]
	v_mfma_f32_16x16x32_bf16 v[116:119], v[168:171], v[184:187], v[116:119]
	v_mfma_f32_16x16x32_bf16 v[112:115], v[176:179], v[184:187], v[112:115]
	v_mfma_f32_16x16x32_bf16 v[100:103], v[168:171], v[194:197], v[100:103]
	v_mfma_f32_16x16x32_bf16 v[96:99], v[176:179], v[194:197], v[96:99]
	v_mfma_f32_16x16x32_bf16 v[84:87], v[168:171], v[202:205], v[84:87]
	v_mfma_f32_16x16x32_bf16 v[80:83], v[176:179], v[202:205], v[80:83]
	v_mfma_f32_16x16x32_bf16 v[68:71], v[168:171], v[210:213], v[68:71]
	v_mfma_f32_16x16x32_bf16 v[64:67], v[176:179], v[210:213], v[64:67]
	s_barrier
	s_add_i32 s36, s54, s14
	v_lshl_add_u64 v[214:215], v[214:215], 0, s[8:9]
	s_mov_b32 m0, s36
	ds_read_b128 v[180:183], v151 offset:49152
	ds_read_b128 v[184:187], v151 offset:50176
	ds_read_b128 v[188:191], v151 offset:51200
	ds_read_b128 v[194:197], v151 offset:52224
	ds_read_b128 v[198:201], v151 offset:53248
	ds_read_b128 v[202:205], v151 offset:54272
	ds_read_b128 v[206:209], v151 offset:55296
	ds_read_b128 v[210:213], v151 offset:56320
	global_load_lds_dwordx4 v[214:215], off
	s_add_i32 m0, s36, 0x2000
	s_add_u32 s34, s34, 0x40080
	v_lshl_add_u64 v[214:215], v[216:217], 0, s[8:9]
	s_addc_u32 s35, s35, 0
	s_add_i32 s36, s55, s14
	global_load_lds_dwordx4 v[214:215], off
	v_lshl_add_u64 v[214:215], s[34:35], 0, v[128:129]
	s_mov_b32 m0, s36
	s_nop 0
	global_load_lds_dwordx4 v[214:215], off
	v_lshl_add_u64 v[214:215], s[34:35], 0, v[130:131]
	s_add_i32 m0, s36, 0x2000
	s_nop 0
	global_load_lds_dwordx4 v[214:215], off
	v_lshl_add_u64 v[214:215], v[218:219], 0, s[8:9]
	s_mov_b32 m0, s45
	s_nop 0
	global_load_lds_dwordx4 v[214:215], off
	v_lshl_add_u64 v[214:215], v[220:221], 0, s[8:9]
	s_mov_b32 m0, s46
	s_nop 0
	global_load_lds_dwordx4 v[214:215], off
	s_waitcnt vmcnt(8)
	s_waitcnt lgkmcnt(0)
	s_barrier
	s_waitcnt lgkmcnt(0)
	v_mfma_f32_16x16x32_bf16 v[60:63], v[140:143], v[180:183], v[60:63]
	v_mfma_f32_16x16x32_bf16 v[56:59], v[156:159], v[180:183], v[56:59]
	v_mfma_f32_16x16x32_bf16 v[44:47], v[140:143], v[188:191], v[44:47]
	v_mfma_f32_16x16x32_bf16 v[40:43], v[156:159], v[188:191], v[40:43]
	v_mfma_f32_16x16x32_bf16 v[28:31], v[140:143], v[198:201], v[28:31]
	v_mfma_f32_16x16x32_bf16 v[24:27], v[156:159], v[198:201], v[24:27]
	v_mfma_f32_16x16x32_bf16 v[12:15], v[140:143], v[206:209], v[12:15]
	v_mfma_f32_16x16x32_bf16 v[8:11], v[156:159], v[206:209], v[8:11]
	v_mfma_f32_16x16x32_bf16 v[60:63], v[152:155], v[184:187], v[60:63]
	v_mfma_f32_16x16x32_bf16 v[56:59], v[160:163], v[184:187], v[56:59]
	v_mfma_f32_16x16x32_bf16 v[44:47], v[152:155], v[194:197], v[44:47]
	v_mfma_f32_16x16x32_bf16 v[40:43], v[160:163], v[194:197], v[40:43]
	v_mfma_f32_16x16x32_bf16 v[28:31], v[152:155], v[202:205], v[28:31]
	v_mfma_f32_16x16x32_bf16 v[24:27], v[160:163], v[202:205], v[24:27]
	v_mfma_f32_16x16x32_bf16 v[12:15], v[152:155], v[210:213], v[12:15]
	v_mfma_f32_16x16x32_bf16 v[8:11], v[160:163], v[210:213], v[8:11]
	v_mfma_f32_16x16x32_bf16 v[52:55], v[164:167], v[180:183], v[52:55]
	v_mfma_f32_16x16x32_bf16 v[48:51], v[172:175], v[180:183], v[48:51]
	v_mfma_f32_16x16x32_bf16 v[36:39], v[164:167], v[188:191], v[36:39]
	v_mfma_f32_16x16x32_bf16 v[32:35], v[172:175], v[188:191], v[32:35]
	v_mfma_f32_16x16x32_bf16 v[20:23], v[164:167], v[198:201], v[20:23]
	v_mfma_f32_16x16x32_bf16 v[16:19], v[172:175], v[198:201], v[16:19]
	v_mfma_f32_16x16x32_bf16 v[4:7], v[164:167], v[206:209], v[4:7]
	v_mfma_f32_16x16x32_bf16 v[0:3], v[172:175], v[206:209], v[0:3]
	v_mfma_f32_16x16x32_bf16 v[52:55], v[168:171], v[184:187], v[52:55]
	v_mfma_f32_16x16x32_bf16 v[48:51], v[176:179], v[184:187], v[48:51]
	v_mfma_f32_16x16x32_bf16 v[36:39], v[168:171], v[194:197], v[36:39]
	v_mfma_f32_16x16x32_bf16 v[32:35], v[176:179], v[194:197], v[32:35]
	v_mfma_f32_16x16x32_bf16 v[20:23], v[168:171], v[202:205], v[20:23]
	v_mfma_f32_16x16x32_bf16 v[16:19], v[176:179], v[202:205], v[16:19]
	v_mfma_f32_16x16x32_bf16 v[4:7], v[168:171], v[210:213], v[4:7]
	v_mfma_f32_16x16x32_bf16 v[0:3], v[176:179], v[210:213], v[0:3]
	s_barrier
	s_add_i32 s53, s53, 2
	s_add_u32 s30, s30, 0x100
	s_addc_u32 s31, s31, 0
	s_add_u32 s51, s51, 0x100
	s_addc_u32 s52, s52, 0
	s_cmp_gt_u32 s53, 13
	s_cbranch_scc0 .LBB0_885
	s_and_b64 vcc, exec, s[10:11]
	s_cbranch_vccz .LBB0_888
	s_barrier

.LBB0_974:
	ds_read_b128 v[154:157], v150
	ds_read_b128 v[158:161], v150 offset:1024
	ds_read_b128 v[162:165], v150 offset:2048
	ds_read_b128 v[166:169], v150 offset:3072
	ds_read_b128 v[170:173], v151
	ds_read_b128 v[174:177], v151 offset:1024
	ds_read_b128 v[178:181], v151 offset:2048
	ds_read_b128 v[182:185], v151 offset:3072
	s_add_u32 s28, s26, 0xfffc0080
	s_addc_u32 s29, s27, -1
	s_cmp_eq_u32 s51, 12
	s_cselect_b32 s31, s17, s29
	s_cselect_b32 s30, s47, s28
	s_cselect_b32 s29, s13, s50
	s_cselect_b32 s28, s48, s49
	v_lshl_add_u64 v[146:147], s[26:27], 0, v[138:139]
	s_add_i32 m0, s33, 0xc000
	ds_read_b128 v[186:189], v152
	ds_read_b128 v[194:197], v152 offset:1024
	ds_read_b128 v[198:201], v152 offset:2048
	ds_read_b128 v[202:205], v152 offset:3072
	ds_read_b128 v[206:209], v152 offset:4096
	ds_read_b128 v[210:213], v152 offset:5120
	ds_read_b128 v[214:217], v152 offset:6144
	ds_read_b128 v[218:221], v152 offset:7168
	global_load_lds_dwordx4 v[146:147], off
	v_lshl_add_u64 v[146:147], s[26:27], 0, v[140:141]
	s_add_i32 m0, s33, 0xe000
	s_nop 0
	global_load_lds_dwordx4 v[146:147], off
	s_waitcnt vmcnt(8)
	s_waitcnt lgkmcnt(0)
	s_barrier
	s_waitcnt lgkmcnt(0)
	v_mfma_f32_16x16x32_bf16 v[124:127], v[154:157], v[186:189], v[124:127]
	v_mfma_f32_16x16x32_bf16 v[120:123], v[162:165], v[186:189], v[120:123]
	v_mfma_f32_16x16x32_bf16 v[108:111], v[154:157], v[198:201], v[108:111]
	v_mfma_f32_16x16x32_bf16 v[104:107], v[162:165], v[198:201], v[104:107]
	v_mfma_f32_16x16x32_bf16 v[92:95], v[154:157], v[206:209], v[92:95]
	v_mfma_f32_16x16x32_bf16 v[88:91], v[162:165], v[206:209], v[88:91]
	v_mfma_f32_16x16x32_bf16 v[76:79], v[154:157], v[214:217], v[76:79]
	v_mfma_f32_16x16x32_bf16 v[72:75], v[162:165], v[214:217], v[72:75]
	v_mfma_f32_16x16x32_bf16 v[124:127], v[158:161], v[194:197], v[124:127]
	v_mfma_f32_16x16x32_bf16 v[120:123], v[166:169], v[194:197], v[120:123]
	v_mfma_f32_16x16x32_bf16 v[108:111], v[158:161], v[202:205], v[108:111]
	v_mfma_f32_16x16x32_bf16 v[104:107], v[166:169], v[202:205], v[104:107]
	v_mfma_f32_16x16x32_bf16 v[92:95], v[158:161], v[210:213], v[92:95]
	v_mfma_f32_16x16x32_bf16 v[88:91], v[166:169], v[210:213], v[88:91]
	v_mfma_f32_16x16x32_bf16 v[76:79], v[158:161], v[218:221], v[76:79]
	v_mfma_f32_16x16x32_bf16 v[72:75], v[166:169], v[218:221], v[72:75]
	v_mfma_f32_16x16x32_bf16 v[116:119], v[170:173], v[186:189], v[116:119]
	v_mfma_f32_16x16x32_bf16 v[112:115], v[178:181], v[186:189], v[112:115]
	v_mfma_f32_16x16x32_bf16 v[100:103], v[170:173], v[198:201], v[100:103]
	v_mfma_f32_16x16x32_bf16 v[96:99], v[178:181], v[198:201], v[96:99]
	v_mfma_f32_16x16x32_bf16 v[84:87], v[170:173], v[206:209], v[84:87]
	v_mfma_f32_16x16x32_bf16 v[80:83], v[178:181], v[206:209], v[80:83]
	v_mfma_f32_16x16x32_bf16 v[68:71], v[170:173], v[214:217], v[68:71]
	v_mfma_f32_16x16x32_bf16 v[64:67], v[178:181], v[214:217], v[64:67]
	v_mfma_f32_16x16x32_bf16 v[116:119], v[174:177], v[194:197], v[116:119]
	v_mfma_f32_16x16x32_bf16 v[112:115], v[182:185], v[194:197], v[112:115]
	v_mfma_f32_16x16x32_bf16 v[100:103], v[174:177], v[202:205], v[100:103]
	v_mfma_f32_16x16x32_bf16 v[96:99], v[182:185], v[202:205], v[96:99]
	v_mfma_f32_16x16x32_bf16 v[84:87], v[174:177], v[210:213], v[84:87]
	v_mfma_f32_16x16x32_bf16 v[80:83], v[182:185], v[210:213], v[80:83]
	v_mfma_f32_16x16x32_bf16 v[68:71], v[174:177], v[218:221], v[68:71]
	v_mfma_f32_16x16x32_bf16 v[64:67], v[182:185], v[218:221], v[64:67]
	s_barrier
	s_add_i32 s52, s43, s14
	v_lshl_add_u64 v[146:147], s[28:29], 0, v[132:133]
	s_mov_b32 m0, s52
	ds_read_b128 v[186:189], v152 offset:16384
	ds_read_b128 v[194:197], v152 offset:17408
	ds_read_b128 v[198:201], v152 offset:18432
	ds_read_b128 v[202:205], v152 offset:19456
	ds_read_b128 v[206:209], v152 offset:20480
	ds_read_b128 v[210:213], v152 offset:21504
	ds_read_b128 v[214:217], v152 offset:22528
	ds_read_b128 v[218:221], v152 offset:23552
	global_load_lds_dwordx4 v[146:147], off
	s_add_i32 m0, s52, 0x2000
	s_add_u32 s52, s28, 0x40000
	v_lshl_add_u64 v[190:191], s[28:29], 0, v[128:129]
	s_addc_u32 s53, s29, 0
	s_add_i32 s54, s44, s14
	global_load_lds_dwordx4 v[190:191], off
	v_lshl_add_u64 v[222:223], s[52:53], 0, v[132:133]
	s_mov_b32 m0, s54
	v_lshl_add_u64 v[224:225], s[30:31], 0, v[130:131]
	global_load_lds_dwordx4 v[222:223], off
	v_lshl_add_u64 v[222:223], s[52:53], 0, v[128:129]
	s_add_i32 m0, s54, 0x2000
	s_nop 0
	global_load_lds_dwordx4 v[222:223], off
	v_lshl_add_u64 v[222:223], s[30:31], 0, v[134:135]
	s_mov_b32 m0, s33
	s_nop 0
	global_load_lds_dwordx4 v[222:223], off
	s_mov_b32 m0, s34
	s_nop 0
	global_load_lds_dwordx4 v[224:225], off
	s_waitcnt vmcnt(8)
	s_waitcnt lgkmcnt(0)
	s_barrier
	s_waitcnt lgkmcnt(0)
	v_mfma_f32_16x16x32_bf16 v[60:63], v[154:157], v[186:189], v[60:63]
	v_mfma_f32_16x16x32_bf16 v[56:59], v[162:165], v[186:189], v[56:59]
	v_mfma_f32_16x16x32_bf16 v[44:47], v[154:157], v[198:201], v[44:47]
	v_mfma_f32_16x16x32_bf16 v[40:43], v[162:165], v[198:201], v[40:43]
	v_mfma_f32_16x16x32_bf16 v[28:31], v[154:157], v[206:209], v[28:31]
	v_mfma_f32_16x16x32_bf16 v[24:27], v[162:165], v[206:209], v[24:27]
	v_mfma_f32_16x16x32_bf16 v[12:15], v[154:157], v[214:217], v[12:15]
	v_mfma_f32_16x16x32_bf16 v[8:11], v[162:165], v[214:217], v[8:11]
	v_mfma_f32_16x16x32_bf16 v[60:63], v[158:161], v[194:197], v[60:63]
	v_mfma_f32_16x16x32_bf16 v[56:59], v[166:169], v[194:197], v[56:59]
	v_mfma_f32_16x16x32_bf16 v[44:47], v[158:161], v[202:205], v[44:47]
	v_mfma_f32_16x16x32_bf16 v[40:43], v[166:169], v[202:205], v[40:43]
	v_mfma_f32_16x16x32_bf16 v[28:31], v[158:161], v[210:213], v[28:31]
	v_mfma_f32_16x16x32_bf16 v[24:27], v[166:169], v[210:213], v[24:27]
	v_mfma_f32_16x16x32_bf16 v[12:15], v[158:161], v[218:221], v[12:15]
	v_mfma_f32_16x16x32_bf16 v[8:11], v[166:169], v[218:221], v[8:11]
	v_mfma_f32_16x16x32_bf16 v[52:55], v[170:173], v[186:189], v[52:55]
	v_mfma_f32_16x16x32_bf16 v[48:51], v[178:181], v[186:189], v[48:51]
	v_mfma_f32_16x16x32_bf16 v[36:39], v[170:173], v[198:201], v[36:39]
	v_mfma_f32_16x16x32_bf16 v[32:35], v[178:181], v[198:201], v[32:35]
	v_mfma_f32_16x16x32_bf16 v[20:23], v[170:173], v[206:209], v[20:23]
	v_mfma_f32_16x16x32_bf16 v[16:19], v[178:181], v[206:209], v[16:19]
	v_mfma_f32_16x16x32_bf16 v[4:7], v[170:173], v[214:217], v[4:7]
	v_mfma_f32_16x16x32_bf16 v[0:3], v[178:181], v[214:217], v[0:3]
	v_mfma_f32_16x16x32_bf16 v[52:55], v[174:177], v[194:197], v[52:55]
	v_mfma_f32_16x16x32_bf16 v[48:51], v[182:185], v[194:197], v[48:51]
	v_mfma_f32_16x16x32_bf16 v[36:39], v[174:177], v[202:205], v[36:39]
	v_mfma_f32_16x16x32_bf16 v[32:35], v[182:185], v[202:205], v[32:35]
	v_mfma_f32_16x16x32_bf16 v[20:23], v[174:177], v[210:213], v[20:23]
	v_mfma_f32_16x16x32_bf16 v[16:19], v[182:185], v[210:213], v[16:19]
	v_mfma_f32_16x16x32_bf16 v[4:7], v[174:177], v[218:221], v[4:7]
	v_mfma_f32_16x16x32_bf16 v[0:3], v[182:185], v[218:221], v[0:3]
	s_barrier
	s_add_i32 s52, 0, 0x18000
	s_add_i32 s53, 0, 0x1c000
	v_add_u32_e32 v166, s52, v149
	v_add_u32_e32 v182, s53, v149
	ds_read_b128 v[154:157], v166
	ds_read_b128 v[158:161], v166 offset:1024
	ds_read_b128 v[162:165], v166 offset:2048
	ds_read_b128 v[166:169], v166 offset:3072
	ds_read_b128 v[170:173], v182
	ds_read_b128 v[174:177], v182 offset:1024
	ds_read_b128 v[178:181], v182 offset:2048
	ds_read_b128 v[182:185], v182 offset:3072
	s_add_u32 s30, s30, 0x40000
	s_addc_u32 s31, s31, 0
	s_mov_b32 m0, s35
	v_lshl_add_u64 v[226:227], s[30:31], 0, v[134:135]
	ds_read_b128 v[186:189], v152 offset:32768
	ds_read_b128 v[194:197], v152 offset:33792
	ds_read_b128 v[198:201], v152 offset:34816
	ds_read_b128 v[202:205], v152 offset:35840
	ds_read_b128 v[206:209], v152 offset:36864
	ds_read_b128 v[210:213], v152 offset:37888
	ds_read_b128 v[214:217], v152 offset:38912
	ds_read_b128 v[218:221], v152 offset:39936
	global_load_lds_dwordx4 v[226:227], off
	v_lshl_add_u64 v[226:227], s[30:31], 0, v[130:131]
	s_mov_b32 m0, s36
	s_nop 0
	global_load_lds_dwordx4 v[226:227], off
	s_waitcnt vmcnt(8)
	s_waitcnt lgkmcnt(0)
	s_barrier
	s_waitcnt lgkmcnt(0)
	v_mfma_f32_16x16x32_bf16 v[124:127], v[154:157], v[186:189], v[124:127]
	v_mfma_f32_16x16x32_bf16 v[120:123], v[162:165], v[186:189], v[120:123]
	v_mfma_f32_16x16x32_bf16 v[108:111], v[154:157], v[198:201], v[108:111]
	v_mfma_f32_16x16x32_bf16 v[104:107], v[162:165], v[198:201], v[104:107]
	v_mfma_f32_16x16x32_bf16 v[92:95], v[154:157], v[206:209], v[92:95]
	v_mfma_f32_16x16x32_bf16 v[88:91], v[162:165], v[206:209], v[88:91]
	v_mfma_f32_16x16x32_bf16 v[76:79], v[154:157], v[214:217], v[76:79]
	v_mfma_f32_16x16x32_bf16 v[72:75], v[162:165], v[214:217], v[72:75]
	v_mfma_f32_16x16x32_bf16 v[124:127], v[158:161], v[194:197], v[124:127]
	v_mfma_f32_16x16x32_bf16 v[120:123], v[166:169], v[194:197], v[120:123]
	v_mfma_f32_16x16x32_bf16 v[108:111], v[158:161], v[202:205], v[108:111]
	v_mfma_f32_16x16x32_bf16 v[104:107], v[166:169], v[202:205], v[104:107]
	v_mfma_f32_16x16x32_bf16 v[92:95], v[158:161], v[210:213], v[92:95]
	v_mfma_f32_16x16x32_bf16 v[88:91], v[166:169], v[210:213], v[88:91]
	v_mfma_f32_16x16x32_bf16 v[76:79], v[158:161], v[218:221], v[76:79]
	v_mfma_f32_16x16x32_bf16 v[72:75], v[166:169], v[218:221], v[72:75]
	v_mfma_f32_16x16x32_bf16 v[116:119], v[170:173], v[186:189], v[116:119]
	v_mfma_f32_16x16x32_bf16 v[112:115], v[178:181], v[186:189], v[112:115]
	v_mfma_f32_16x16x32_bf16 v[100:103], v[170:173], v[198:201], v[100:103]
	v_mfma_f32_16x16x32_bf16 v[96:99], v[178:181], v[198:201], v[96:99]
	v_mfma_f32_16x16x32_bf16 v[84:87], v[170:173], v[206:209], v[84:87]
	v_mfma_f32_16x16x32_bf16 v[80:83], v[178:181], v[206:209], v[80:83]
	v_mfma_f32_16x16x32_bf16 v[68:71], v[170:173], v[214:217], v[68:71]
	v_mfma_f32_16x16x32_bf16 v[64:67], v[178:181], v[214:217], v[64:67]
	v_mfma_f32_16x16x32_bf16 v[116:119], v[174:177], v[194:197], v[116:119]
	v_mfma_f32_16x16x32_bf16 v[112:115], v[182:185], v[194:197], v[112:115]
	v_mfma_f32_16x16x32_bf16 v[100:103], v[174:177], v[202:205], v[100:103]
	v_mfma_f32_16x16x32_bf16 v[96:99], v[182:185], v[202:205], v[96:99]
	v_mfma_f32_16x16x32_bf16 v[84:87], v[174:177], v[210:213], v[84:87]
	v_mfma_f32_16x16x32_bf16 v[80:83], v[182:185], v[210:213], v[80:83]
	v_mfma_f32_16x16x32_bf16 v[68:71], v[174:177], v[218:221], v[68:71]
	v_mfma_f32_16x16x32_bf16 v[64:67], v[182:185], v[218:221], v[64:67]
	s_barrier
	s_add_i32 s30, s52, s14
	v_lshl_add_u64 v[146:147], v[146:147], 0, s[6:7]
	s_mov_b32 m0, s30
	ds_read_b128 v[186:189], v152 offset:49152
	ds_read_b128 v[194:197], v152 offset:50176
	ds_read_b128 v[198:201], v152 offset:51200
	ds_read_b128 v[202:205], v152 offset:52224
	ds_read_b128 v[206:209], v152 offset:53248
	ds_read_b128 v[210:213], v152 offset:54272
	ds_read_b128 v[214:217], v152 offset:55296
	ds_read_b128 v[218:221], v152 offset:56320
	global_load_lds_dwordx4 v[146:147], off
	s_add_i32 m0, s30, 0x2000
	s_add_u32 s28, s28, 0x40080
	v_lshl_add_u64 v[146:147], v[190:191], 0, s[6:7]
	s_addc_u32 s29, s29, 0
	s_add_i32 s30, s53, s14
	global_load_lds_dwordx4 v[146:147], off
	v_lshl_add_u64 v[146:147], s[28:29], 0, v[132:133]
	s_mov_b32 m0, s30
	s_nop 0
	global_load_lds_dwordx4 v[146:147], off
	v_lshl_add_u64 v[146:147], s[28:29], 0, v[128:129]
	s_add_i32 m0, s30, 0x2000
	s_nop 0
	global_load_lds_dwordx4 v[146:147], off
	v_lshl_add_u64 v[146:147], v[222:223], 0, s[6:7]
	s_mov_b32 m0, s37
	s_nop 0
	global_load_lds_dwordx4 v[146:147], off
	v_lshl_add_u64 v[146:147], v[224:225], 0, s[6:7]
	s_mov_b32 m0, s42
	s_nop 0
	global_load_lds_dwordx4 v[146:147], off
	s_waitcnt vmcnt(8)
	s_waitcnt lgkmcnt(0)
	s_barrier
	s_waitcnt lgkmcnt(0)
	v_mfma_f32_16x16x32_bf16 v[60:63], v[154:157], v[186:189], v[60:63]
	v_mfma_f32_16x16x32_bf16 v[56:59], v[162:165], v[186:189], v[56:59]
	v_mfma_f32_16x16x32_bf16 v[44:47], v[154:157], v[198:201], v[44:47]
	v_mfma_f32_16x16x32_bf16 v[40:43], v[162:165], v[198:201], v[40:43]
	v_mfma_f32_16x16x32_bf16 v[28:31], v[154:157], v[206:209], v[28:31]
	v_mfma_f32_16x16x32_bf16 v[24:27], v[162:165], v[206:209], v[24:27]
	v_mfma_f32_16x16x32_bf16 v[12:15], v[154:157], v[214:217], v[12:15]
	v_mfma_f32_16x16x32_bf16 v[8:11], v[162:165], v[214:217], v[8:11]
	v_mfma_f32_16x16x32_bf16 v[60:63], v[158:161], v[194:197], v[60:63]
	v_mfma_f32_16x16x32_bf16 v[56:59], v[166:169], v[194:197], v[56:59]
	v_mfma_f32_16x16x32_bf16 v[44:47], v[158:161], v[202:205], v[44:47]
	v_mfma_f32_16x16x32_bf16 v[40:43], v[166:169], v[202:205], v[40:43]
	v_mfma_f32_16x16x32_bf16 v[28:31], v[158:161], v[210:213], v[28:31]
	v_mfma_f32_16x16x32_bf16 v[24:27], v[166:169], v[210:213], v[24:27]
	v_mfma_f32_16x16x32_bf16 v[12:15], v[158:161], v[218:221], v[12:15]
	v_mfma_f32_16x16x32_bf16 v[8:11], v[166:169], v[218:221], v[8:11]
	v_mfma_f32_16x16x32_bf16 v[52:55], v[170:173], v[186:189], v[52:55]
	v_mfma_f32_16x16x32_bf16 v[48:51], v[178:181], v[186:189], v[48:51]
	v_mfma_f32_16x16x32_bf16 v[36:39], v[170:173], v[198:201], v[36:39]
	v_mfma_f32_16x16x32_bf16 v[32:35], v[178:181], v[198:201], v[32:35]
	v_mfma_f32_16x16x32_bf16 v[20:23], v[170:173], v[206:209], v[20:23]
	v_mfma_f32_16x16x32_bf16 v[16:19], v[178:181], v[206:209], v[16:19]
	v_mfma_f32_16x16x32_bf16 v[4:7], v[170:173], v[214:217], v[4:7]
	v_mfma_f32_16x16x32_bf16 v[0:3], v[178:181], v[214:217], v[0:3]
	v_mfma_f32_16x16x32_bf16 v[52:55], v[174:177], v[194:197], v[52:55]
	v_mfma_f32_16x16x32_bf16 v[48:51], v[182:185], v[194:197], v[48:51]
	v_mfma_f32_16x16x32_bf16 v[36:39], v[174:177], v[202:205], v[36:39]
	v_mfma_f32_16x16x32_bf16 v[32:35], v[182:185], v[202:205], v[32:35]
	v_mfma_f32_16x16x32_bf16 v[20:23], v[174:177], v[210:213], v[20:23]
	v_mfma_f32_16x16x32_bf16 v[16:19], v[182:185], v[210:213], v[16:19]
	v_mfma_f32_16x16x32_bf16 v[4:7], v[174:177], v[218:221], v[4:7]
	v_mfma_f32_16x16x32_bf16 v[0:3], v[182:185], v[218:221], v[0:3]
	s_barrier
	s_add_i32 s51, s51, 2
	s_add_u32 s26, s26, 0x100
	s_addc_u32 s27, s27, 0
	s_add_u32 s49, s49, 0x100
	s_addc_u32 s50, s50, 0
	s_cmp_gt_u32 s51, 13
	s_cbranch_scc0 .LBB0_974
	s_and_b64 vcc, exec, s[10:11]
	s_cbranch_vccz .LBB0_977
	s_barrier

.LBB0_1055:
	ds_read_b128 v[142:145], v147
	ds_read_b128 v[150:153], v147 offset:1024
	ds_read_b128 v[154:157], v147 offset:2048
	ds_read_b128 v[158:161], v147 offset:3072
	ds_read_b128 v[162:165], v148
	ds_read_b128 v[166:169], v148 offset:1024
	ds_read_b128 v[170:173], v148 offset:2048
	ds_read_b128 v[174:177], v148 offset:3072
	s_add_u32 s16, s14, 0x100
	s_addc_u32 s17, s15, 0
	s_cmp_eq_u32 s39, 40
	s_cselect_b32 s21, s5, s17
	s_cselect_b32 s20, s4, s16
	s_cselect_b32 s19, s13, s38
	s_cselect_b32 s18, s12, s37
	v_lshl_add_u64 v[210:211], s[14:15], 0, v[134:135]
	s_add_i32 m0, s23, 0xc000
	ds_read_b128 v[178:181], v149
	ds_read_b128 v[182:185], v149 offset:1024
	ds_read_b128 v[186:189], v149 offset:2048
	ds_read_b128 v[190:193], v149 offset:3072
	ds_read_b128 v[194:197], v149 offset:4096
	ds_read_b128 v[198:201], v149 offset:5120
	ds_read_b128 v[202:205], v149 offset:6144
	ds_read_b128 v[206:209], v149 offset:7168
	global_load_lds_dwordx4 v[210:211], off
	v_lshl_add_u64 v[210:211], s[14:15], 0, v[136:137]
	s_add_i32 m0, s23, 0xe000
	s_nop 0
	global_load_lds_dwordx4 v[210:211], off
	s_waitcnt vmcnt(8)
	s_waitcnt lgkmcnt(0)
	s_barrier
	s_waitcnt lgkmcnt(0)
	v_mfma_f32_16x16x32_bf16 v[124:127], v[142:145], v[178:181], v[124:127]
	v_mfma_f32_16x16x32_bf16 v[120:123], v[154:157], v[178:181], v[120:123]
	v_mfma_f32_16x16x32_bf16 v[108:111], v[142:145], v[186:189], v[108:111]
	v_mfma_f32_16x16x32_bf16 v[104:107], v[154:157], v[186:189], v[104:107]
	v_mfma_f32_16x16x32_bf16 v[92:95], v[142:145], v[194:197], v[92:95]
	v_mfma_f32_16x16x32_bf16 v[88:91], v[154:157], v[194:197], v[88:91]
	v_mfma_f32_16x16x32_bf16 v[76:79], v[142:145], v[202:205], v[76:79]
	v_mfma_f32_16x16x32_bf16 v[72:75], v[154:157], v[202:205], v[72:75]
	v_mfma_f32_16x16x32_bf16 v[124:127], v[150:153], v[182:185], v[124:127]
	v_mfma_f32_16x16x32_bf16 v[120:123], v[158:161], v[182:185], v[120:123]
	v_mfma_f32_16x16x32_bf16 v[108:111], v[150:153], v[190:193], v[108:111]
	v_mfma_f32_16x16x32_bf16 v[104:107], v[158:161], v[190:193], v[104:107]
	v_mfma_f32_16x16x32_bf16 v[92:95], v[150:153], v[198:201], v[92:95]
	v_mfma_f32_16x16x32_bf16 v[88:91], v[158:161], v[198:201], v[88:91]
	v_mfma_f32_16x16x32_bf16 v[76:79], v[150:153], v[206:209], v[76:79]
	v_mfma_f32_16x16x32_bf16 v[72:75], v[158:161], v[206:209], v[72:75]
	v_mfma_f32_16x16x32_bf16 v[116:119], v[162:165], v[178:181], v[116:119]
	v_mfma_f32_16x16x32_bf16 v[112:115], v[170:173], v[178:181], v[112:115]
	v_mfma_f32_16x16x32_bf16 v[100:103], v[162:165], v[186:189], v[100:103]
	v_mfma_f32_16x16x32_bf16 v[96:99], v[170:173], v[186:189], v[96:99]
	v_mfma_f32_16x16x32_bf16 v[84:87], v[162:165], v[194:197], v[84:87]
	v_mfma_f32_16x16x32_bf16 v[80:83], v[170:173], v[194:197], v[80:83]
	v_mfma_f32_16x16x32_bf16 v[68:71], v[162:165], v[202:205], v[68:71]
	v_mfma_f32_16x16x32_bf16 v[64:67], v[170:173], v[202:205], v[64:67]
	v_mfma_f32_16x16x32_bf16 v[116:119], v[166:169], v[182:185], v[116:119]
	v_mfma_f32_16x16x32_bf16 v[112:115], v[174:177], v[182:185], v[112:115]
	v_mfma_f32_16x16x32_bf16 v[100:103], v[166:169], v[190:193], v[100:103]
	v_mfma_f32_16x16x32_bf16 v[96:99], v[174:177], v[190:193], v[96:99]
	v_mfma_f32_16x16x32_bf16 v[84:87], v[166:169], v[198:201], v[84:87]
	v_mfma_f32_16x16x32_bf16 v[80:83], v[174:177], v[198:201], v[80:83]
	v_mfma_f32_16x16x32_bf16 v[68:71], v[166:169], v[206:209], v[68:71]
	v_mfma_f32_16x16x32_bf16 v[64:67], v[174:177], v[206:209], v[64:67]
	s_barrier
	s_add_i32 s14, s30, s22
	v_lshl_add_u64 v[210:211], s[18:19], 0, v[130:131]
	s_mov_b32 m0, s14
	ds_read_b128 v[178:181], v149 offset:16384
	ds_read_b128 v[182:185], v149 offset:17408
	ds_read_b128 v[186:189], v149 offset:18432
	ds_read_b128 v[190:193], v149 offset:19456
	ds_read_b128 v[194:197], v149 offset:20480
	ds_read_b128 v[198:201], v149 offset:21504
	ds_read_b128 v[202:205], v149 offset:22528
	ds_read_b128 v[206:209], v149 offset:23552
	global_load_lds_dwordx4 v[210:211], off
	s_add_i32 m0, s14, 0x2000
	s_add_u32 s14, s18, 0xb0000
	v_lshl_add_u64 v[212:213], s[18:19], 0, v[128:129]
	s_addc_u32 s15, s19, 0
	s_add_i32 s40, s31, s22
	global_load_lds_dwordx4 v[212:213], off
	v_lshl_add_u64 v[214:215], s[14:15], 0, v[130:131]
	s_mov_b32 m0, s40
	v_lshl_add_u64 v[216:217], s[20:21], 0, v[128:129]
	global_load_lds_dwordx4 v[214:215], off
	v_lshl_add_u64 v[214:215], s[14:15], 0, v[128:129]
	s_add_i32 m0, s40, 0x2000
	s_nop 0
	global_load_lds_dwordx4 v[214:215], off
	v_lshl_add_u64 v[214:215], s[20:21], 0, v[130:131]
	s_mov_b32 m0, s23
	s_nop 0
	global_load_lds_dwordx4 v[214:215], off
	s_mov_b32 m0, s24
	s_nop 0
	global_load_lds_dwordx4 v[216:217], off
	s_waitcnt vmcnt(8)
	s_waitcnt lgkmcnt(0)
	s_barrier
	s_waitcnt lgkmcnt(0)
	v_mfma_f32_16x16x32_bf16 v[60:63], v[142:145], v[178:181], v[60:63]
	v_mfma_f32_16x16x32_bf16 v[56:59], v[154:157], v[178:181], v[56:59]
	v_mfma_f32_16x16x32_bf16 v[44:47], v[142:145], v[186:189], v[44:47]
	v_mfma_f32_16x16x32_bf16 v[40:43], v[154:157], v[186:189], v[40:43]
	v_mfma_f32_16x16x32_bf16 v[28:31], v[142:145], v[194:197], v[28:31]
	v_mfma_f32_16x16x32_bf16 v[24:27], v[154:157], v[194:197], v[24:27]
	v_mfma_f32_16x16x32_bf16 v[12:15], v[142:145], v[202:205], v[12:15]
	v_mfma_f32_16x16x32_bf16 v[8:11], v[154:157], v[202:205], v[8:11]
	v_mfma_f32_16x16x32_bf16 v[60:63], v[150:153], v[182:185], v[60:63]
	v_mfma_f32_16x16x32_bf16 v[56:59], v[158:161], v[182:185], v[56:59]
	v_mfma_f32_16x16x32_bf16 v[44:47], v[150:153], v[190:193], v[44:47]
	v_mfma_f32_16x16x32_bf16 v[40:43], v[158:161], v[190:193], v[40:43]
	v_mfma_f32_16x16x32_bf16 v[28:31], v[150:153], v[198:201], v[28:31]
	v_mfma_f32_16x16x32_bf16 v[24:27], v[158:161], v[198:201], v[24:27]
	v_mfma_f32_16x16x32_bf16 v[12:15], v[150:153], v[206:209], v[12:15]
	v_mfma_f32_16x16x32_bf16 v[8:11], v[158:161], v[206:209], v[8:11]
	v_mfma_f32_16x16x32_bf16 v[52:55], v[162:165], v[178:181], v[52:55]
	v_mfma_f32_16x16x32_bf16 v[48:51], v[170:173], v[178:181], v[48:51]
	v_mfma_f32_16x16x32_bf16 v[36:39], v[162:165], v[186:189], v[36:39]
	v_mfma_f32_16x16x32_bf16 v[32:35], v[170:173], v[186:189], v[32:35]
	v_mfma_f32_16x16x32_bf16 v[20:23], v[162:165], v[194:197], v[20:23]
	v_mfma_f32_16x16x32_bf16 v[16:19], v[170:173], v[194:197], v[16:19]
	v_mfma_f32_16x16x32_bf16 v[4:7], v[162:165], v[202:205], v[4:7]
	v_mfma_f32_16x16x32_bf16 v[0:3], v[170:173], v[202:205], v[0:3]
	v_mfma_f32_16x16x32_bf16 v[52:55], v[166:169], v[182:185], v[52:55]
	v_mfma_f32_16x16x32_bf16 v[48:51], v[174:177], v[182:185], v[48:51]
	v_mfma_f32_16x16x32_bf16 v[36:39], v[166:169], v[190:193], v[36:39]
	v_mfma_f32_16x16x32_bf16 v[32:35], v[174:177], v[190:193], v[32:35]
	v_mfma_f32_16x16x32_bf16 v[20:23], v[166:169], v[198:201], v[20:23]
	v_mfma_f32_16x16x32_bf16 v[16:19], v[174:177], v[198:201], v[16:19]
	v_mfma_f32_16x16x32_bf16 v[4:7], v[166:169], v[206:209], v[4:7]
	v_mfma_f32_16x16x32_bf16 v[0:3], v[174:177], v[206:209], v[0:3]
	s_barrier
	s_add_i32 s40, 0, 0x18000
	s_add_i32 s41, 0, 0x1c000
	v_add_u32_e32 v158, s40, v146
	v_add_u32_e32 v174, s41, v146
	ds_read_b128 v[142:145], v158
	ds_read_b128 v[150:153], v158 offset:1024
	ds_read_b128 v[154:157], v158 offset:2048
	ds_read_b128 v[158:161], v158 offset:3072
	ds_read_b128 v[162:165], v174
	ds_read_b128 v[166:169], v174 offset:1024
	ds_read_b128 v[170:173], v174 offset:2048
	ds_read_b128 v[174:177], v174 offset:3072
	s_add_u32 s14, s20, 0xb0000
	s_addc_u32 s15, s21, 0
	s_mov_b32 m0, s25
	v_lshl_add_u64 v[218:219], s[14:15], 0, v[130:131]
	ds_read_b128 v[178:181], v149 offset:32768
	ds_read_b128 v[182:185], v149 offset:33792
	ds_read_b128 v[186:189], v149 offset:34816
	ds_read_b128 v[190:193], v149 offset:35840
	ds_read_b128 v[194:197], v149 offset:36864
	ds_read_b128 v[198:201], v149 offset:37888
	ds_read_b128 v[202:205], v149 offset:38912
	ds_read_b128 v[206:209], v149 offset:39936
	global_load_lds_dwordx4 v[218:219], off
	v_lshl_add_u64 v[218:219], s[14:15], 0, v[128:129]
	s_mov_b32 m0, s26
	s_nop 0
	global_load_lds_dwordx4 v[218:219], off
	s_waitcnt vmcnt(8)
	s_waitcnt lgkmcnt(0)
	s_barrier
	s_waitcnt lgkmcnt(0)
	v_mfma_f32_16x16x32_bf16 v[124:127], v[142:145], v[178:181], v[124:127]
	v_mfma_f32_16x16x32_bf16 v[120:123], v[154:157], v[178:181], v[120:123]
	v_mfma_f32_16x16x32_bf16 v[108:111], v[142:145], v[186:189], v[108:111]
	v_mfma_f32_16x16x32_bf16 v[104:107], v[154:157], v[186:189], v[104:107]
	v_mfma_f32_16x16x32_bf16 v[92:95], v[142:145], v[194:197], v[92:95]
	v_mfma_f32_16x16x32_bf16 v[88:91], v[154:157], v[194:197], v[88:91]
	v_mfma_f32_16x16x32_bf16 v[76:79], v[142:145], v[202:205], v[76:79]
	v_mfma_f32_16x16x32_bf16 v[72:75], v[154:157], v[202:205], v[72:75]
	v_mfma_f32_16x16x32_bf16 v[124:127], v[150:153], v[182:185], v[124:127]
	v_mfma_f32_16x16x32_bf16 v[120:123], v[158:161], v[182:185], v[120:123]
	v_mfma_f32_16x16x32_bf16 v[108:111], v[150:153], v[190:193], v[108:111]
	v_mfma_f32_16x16x32_bf16 v[104:107], v[158:161], v[190:193], v[104:107]
	v_mfma_f32_16x16x32_bf16 v[92:95], v[150:153], v[198:201], v[92:95]
	v_mfma_f32_16x16x32_bf16 v[88:91], v[158:161], v[198:201], v[88:91]
	v_mfma_f32_16x16x32_bf16 v[76:79], v[150:153], v[206:209], v[76:79]
	v_mfma_f32_16x16x32_bf16 v[72:75], v[158:161], v[206:209], v[72:75]
	v_mfma_f32_16x16x32_bf16 v[116:119], v[162:165], v[178:181], v[116:119]
	v_mfma_f32_16x16x32_bf16 v[112:115], v[170:173], v[178:181], v[112:115]
	v_mfma_f32_16x16x32_bf16 v[100:103], v[162:165], v[186:189], v[100:103]
	v_mfma_f32_16x16x32_bf16 v[96:99], v[170:173], v[186:189], v[96:99]
	v_mfma_f32_16x16x32_bf16 v[84:87], v[162:165], v[194:197], v[84:87]
	v_mfma_f32_16x16x32_bf16 v[80:83], v[170:173], v[194:197], v[80:83]
	v_mfma_f32_16x16x32_bf16 v[68:71], v[162:165], v[202:205], v[68:71]
	v_mfma_f32_16x16x32_bf16 v[64:67], v[170:173], v[202:205], v[64:67]
	v_mfma_f32_16x16x32_bf16 v[116:119], v[166:169], v[182:185], v[116:119]
	v_mfma_f32_16x16x32_bf16 v[112:115], v[174:177], v[182:185], v[112:115]
	v_mfma_f32_16x16x32_bf16 v[100:103], v[166:169], v[190:193], v[100:103]
	v_mfma_f32_16x16x32_bf16 v[96:99], v[174:177], v[190:193], v[96:99]
	v_mfma_f32_16x16x32_bf16 v[84:87], v[166:169], v[198:201], v[84:87]
	v_mfma_f32_16x16x32_bf16 v[80:83], v[174:177], v[198:201], v[80:83]
	v_mfma_f32_16x16x32_bf16 v[68:71], v[166:169], v[206:209], v[68:71]
	v_mfma_f32_16x16x32_bf16 v[64:67], v[174:177], v[206:209], v[64:67]
	s_barrier
	s_add_i32 s14, s40, s22
	v_lshl_add_u64 v[210:211], v[210:211], 0, s[8:9]
	s_mov_b32 m0, s14
	ds_read_b128 v[178:181], v149 offset:49152
	ds_read_b128 v[182:185], v149 offset:50176
	ds_read_b128 v[186:189], v149 offset:51200
	ds_read_b128 v[190:193], v149 offset:52224
	ds_read_b128 v[194:197], v149 offset:53248
	ds_read_b128 v[198:201], v149 offset:54272
	ds_read_b128 v[202:205], v149 offset:55296
	ds_read_b128 v[206:209], v149 offset:56320
	global_load_lds_dwordx4 v[210:211], off
	s_add_i32 m0, s14, 0x2000
	s_add_u32 s14, s18, 0xb0080
	v_lshl_add_u64 v[210:211], v[212:213], 0, s[8:9]
	s_addc_u32 s15, s19, 0
	s_add_i32 s18, s41, s22
	global_load_lds_dwordx4 v[210:211], off
	v_lshl_add_u64 v[210:211], s[14:15], 0, v[130:131]
	s_mov_b32 m0, s18
	s_nop 0
	global_load_lds_dwordx4 v[210:211], off
	v_lshl_add_u64 v[210:211], s[14:15], 0, v[128:129]
	s_add_i32 m0, s18, 0x2000
	s_nop 0
	global_load_lds_dwordx4 v[210:211], off
	v_lshl_add_u64 v[210:211], v[214:215], 0, s[8:9]
	s_mov_b32 m0, s27
	s_nop 0
	global_load_lds_dwordx4 v[210:211], off
	v_lshl_add_u64 v[210:211], v[216:217], 0, s[8:9]
	s_mov_b32 m0, s28
	s_nop 0
	global_load_lds_dwordx4 v[210:211], off
	s_waitcnt vmcnt(8)
	s_waitcnt lgkmcnt(0)
	s_barrier
	s_waitcnt lgkmcnt(0)
	v_mfma_f32_16x16x32_bf16 v[60:63], v[142:145], v[178:181], v[60:63]
	v_mfma_f32_16x16x32_bf16 v[56:59], v[154:157], v[178:181], v[56:59]
	v_mfma_f32_16x16x32_bf16 v[44:47], v[142:145], v[186:189], v[44:47]
	v_mfma_f32_16x16x32_bf16 v[40:43], v[154:157], v[186:189], v[40:43]
	v_mfma_f32_16x16x32_bf16 v[28:31], v[142:145], v[194:197], v[28:31]
	v_mfma_f32_16x16x32_bf16 v[24:27], v[154:157], v[194:197], v[24:27]
	v_mfma_f32_16x16x32_bf16 v[12:15], v[142:145], v[202:205], v[12:15]
	v_mfma_f32_16x16x32_bf16 v[8:11], v[154:157], v[202:205], v[8:11]
	v_mfma_f32_16x16x32_bf16 v[60:63], v[150:153], v[182:185], v[60:63]
	v_mfma_f32_16x16x32_bf16 v[56:59], v[158:161], v[182:185], v[56:59]
	v_mfma_f32_16x16x32_bf16 v[44:47], v[150:153], v[190:193], v[44:47]
	v_mfma_f32_16x16x32_bf16 v[40:43], v[158:161], v[190:193], v[40:43]
	v_mfma_f32_16x16x32_bf16 v[28:31], v[150:153], v[198:201], v[28:31]
	v_mfma_f32_16x16x32_bf16 v[24:27], v[158:161], v[198:201], v[24:27]
	v_mfma_f32_16x16x32_bf16 v[12:15], v[150:153], v[206:209], v[12:15]
	v_mfma_f32_16x16x32_bf16 v[8:11], v[158:161], v[206:209], v[8:11]
	v_mfma_f32_16x16x32_bf16 v[52:55], v[162:165], v[178:181], v[52:55]
	v_mfma_f32_16x16x32_bf16 v[48:51], v[170:173], v[178:181], v[48:51]
	v_mfma_f32_16x16x32_bf16 v[36:39], v[162:165], v[186:189], v[36:39]
	v_mfma_f32_16x16x32_bf16 v[32:35], v[170:173], v[186:189], v[32:35]
	v_mfma_f32_16x16x32_bf16 v[20:23], v[162:165], v[194:197], v[20:23]
	v_mfma_f32_16x16x32_bf16 v[16:19], v[170:173], v[194:197], v[16:19]
	v_mfma_f32_16x16x32_bf16 v[4:7], v[162:165], v[202:205], v[4:7]
	v_mfma_f32_16x16x32_bf16 v[0:3], v[170:173], v[202:205], v[0:3]
	v_mfma_f32_16x16x32_bf16 v[52:55], v[166:169], v[182:185], v[52:55]
	v_mfma_f32_16x16x32_bf16 v[48:51], v[174:177], v[182:185], v[48:51]
	v_mfma_f32_16x16x32_bf16 v[36:39], v[166:169], v[190:193], v[36:39]
	v_mfma_f32_16x16x32_bf16 v[32:35], v[174:177], v[190:193], v[32:35]
	v_mfma_f32_16x16x32_bf16 v[20:23], v[166:169], v[198:201], v[20:23]
	v_mfma_f32_16x16x32_bf16 v[16:19], v[174:177], v[198:201], v[16:19]
	v_mfma_f32_16x16x32_bf16 v[4:7], v[166:169], v[206:209], v[4:7]
	v_mfma_f32_16x16x32_bf16 v[0:3], v[174:177], v[206:209], v[0:3]
	s_barrier
	s_add_i32 s39, s39, 2
	s_add_u32 s37, s37, 0x100
	s_addc_u32 s38, s38, 0
	s_cmp_gt_u32 s39, 41
	s_mov_b64 s[14:15], s[16:17]
	s_cbranch_scc0 .LBB0_1055
	s_and_b64 vcc, exec, s[10:11]
	s_cbranch_vccz .LBB0_1058
	s_barrier
